# A/B: per-phase s_setprio flips deleted from the five GEMM K-loops
# speedup vs baseline: 1.0058x; 1.0033x over previous
; #define PG8_STAGE(bufoff, gbase, voff) do { _Pragma("unroll") for (int _i = 0; _i < 2; ++_i) \
;         __builtin_amdgcn_global_load_lds((const unsigned*)((const char*)(gbase) + (voff)[_i]), (PG8_LAS unsigned*)(lds + (bufoff) + ldsw + _i * 8192), 16, 0, 0); } while (0)
; #define PG8_LDA(dst, b, h) do { _Pragma("unroll") for (int m = 0; m < 4; ++m) _Pragma("unroll") for (int k = 0; k < 2; ++k) dst[m][k] = *(const PG8_LAS bf16x8*)(lds + PG8_SA(b, h) + aoff + m * 2048 + k * 1024); } while (0)
; #define PG8_LDB(dst, b, h) do { _Pragma("unroll") for (int n = 0; n < 2; ++n) _Pragma("unroll") for (int k = 0; k < 2; ++k) dst[n][k] = *(const PG8_LAS bf16x8*)(lds + PG8_SB(b, h) + boff + n * 2048 + k * 1024); } while (0)
; #define PG8_WAIT_V(n) asm volatile("s_waitcnt vmcnt(" #n ")" ::: "memory")
; #define PG8_WAIT_L(n) asm volatile("s_waitcnt lgkmcnt(" #n ")" ::: "memory")
; #define PG8_BAR __builtin_amdgcn_s_barrier()
; #define PG8_SCHED __builtin_amdgcn_sched_barrier(0)
; template <class Epi, class Sched, bool ALIGN_EPI = false, bool SP2 = false, bool F16 = false>
; __device__ __forceinline__ void gemm_phase(PG8_LAS unsigned char* lds, const Gemm g, const Sched& S, const Epi& E) {
;     ...
;             if constexpr (SP2) {
;             PG8_LDB(B0, 0, 0); PG8_LDB(B1, 0, 1); PG8_SCHED; PG8_LDA(At, 0, 0); PG8_STAGE(PG8_SA(1, 1), a1 + hstep, voffA);
;             PG8_WAIT_V(8); PG8_WAIT_L(0); PG8_BAR; PG8_MMA(0, 0, At, B0); PG8_MMA(0, 1, At, B1); PG8_BAR; PG8_SCHED;
;             PG8_LDA(At, 0, 1); PG8_STAGE(PG8_SB(0, 0), b2, voffB); PG8_STAGE(PG8_SB(0, 1), b2 + hstep, voffB); PG8_STAGE(PG8_SA(0, 0), a2, voffA);
;             PG8_WAIT_V(8); PG8_WAIT_L(0); PG8_BAR; PG8_MMA(1, 0, At, B0); PG8_MMA(1, 1, At, B1); PG8_BAR; PG8_SCHED;
.LBB0_102:
	s_add_u32 s31, s56, 0xfffc0080
	s_addc_u32 s58, s57, -1
	s_add_i32 s90, 0, 0x10000
	s_cmp_eq_u32 s30, 12
	s_cselect_b32 s63, s51, s58
	s_cselect_b32 s62, s64, s31
	v_add_u32_e32 v146, s90, v186
	s_cselect_b32 s59, s49, vcc_hi
	s_cselect_b32 s58, s65, vcc_lo
	s_add_i32 s31, 0, 0x14000
	ds_read_b128 v[128:131], v146
	ds_read_b128 v[156:159], v146 offset:1024
	ds_read_b128 v[160:163], v146 offset:2048
	ds_read_b128 v[164:167], v146 offset:3072
	v_add_u32_e32 v146, s31, v186
	ds_read_b128 v[190:193], v146
	ds_read_b128 v[194:197], v146 offset:1024
	ds_read_b128 v[198:201], v146 offset:2048
	ds_read_b128 v[202:205], v146 offset:3072
	v_lshl_add_u64 v[146:147], s[56:57], 0, v[142:143]
	s_add_i32 m0, s76, 0xc000
	ds_read_b128 v[206:209], v188
	ds_read_b128 v[210:213], v188 offset:1024
	ds_read_b128 v[214:217], v188 offset:2048
	ds_read_b128 v[218:221], v188 offset:3072
	ds_read_b128 v[222:225], v188 offset:4096
	ds_read_b128 v[226:229], v188 offset:5120
	ds_read_b128 v[230:233], v188 offset:6144
	ds_read_b128 v[234:237], v188 offset:7168
	global_load_lds_dwordx4 v[146:147], off
	v_lshl_add_u64 v[146:147], s[56:57], 0, v[144:145]
	s_add_i32 m0, s76, 0xe000
	s_nop 0
	global_load_lds_dwordx4 v[146:147], off
	s_waitcnt vmcnt(8)
	s_waitcnt lgkmcnt(0)
	s_barrier
	s_waitcnt lgkmcnt(0)
	v_mfma_f32_16x16x32_f16 v[124:127], v[128:131], v[206:209], v[124:127]
	v_mfma_f32_16x16x32_f16 v[120:123], v[160:163], v[206:209], v[120:123]
	v_mfma_f32_16x16x32_f16 v[112:115], v[128:131], v[214:217], v[112:115]
	v_mfma_f32_16x16x32_f16 v[104:107], v[160:163], v[214:217], v[104:107]
	v_mfma_f32_16x16x32_f16 v[96:99], v[128:131], v[222:225], v[96:99]
	v_mfma_f32_16x16x32_f16 v[88:91], v[160:163], v[222:225], v[88:91]
	v_mfma_f32_16x16x32_f16 v[80:83], v[128:131], v[230:233], v[80:83]
	v_mfma_f32_16x16x32_f16 v[72:75], v[160:163], v[230:233], v[72:75]
	v_mfma_f32_16x16x32_f16 v[124:127], v[156:159], v[210:213], v[124:127]
	v_mfma_f32_16x16x32_f16 v[120:123], v[164:167], v[210:213], v[120:123]
	v_mfma_f32_16x16x32_f16 v[112:115], v[156:159], v[218:221], v[112:115]
	v_mfma_f32_16x16x32_f16 v[104:107], v[164:167], v[218:221], v[104:107]
	v_mfma_f32_16x16x32_f16 v[96:99], v[156:159], v[226:229], v[96:99]
	v_mfma_f32_16x16x32_f16 v[88:91], v[164:167], v[226:229], v[88:91]
	v_mfma_f32_16x16x32_f16 v[80:83], v[156:159], v[234:237], v[80:83]
	v_mfma_f32_16x16x32_f16 v[72:75], v[164:167], v[234:237], v[72:75]
	v_mfma_f32_16x16x32_f16 v[116:119], v[190:193], v[206:209], v[116:119]
	v_mfma_f32_16x16x32_f16 v[108:111], v[198:201], v[206:209], v[108:111]
	v_mfma_f32_16x16x32_f16 v[100:103], v[190:193], v[214:217], v[100:103]
	v_mfma_f32_16x16x32_f16 v[92:95], v[198:201], v[214:217], v[92:95]
	v_mfma_f32_16x16x32_f16 v[84:87], v[190:193], v[222:225], v[84:87]
	v_mfma_f32_16x16x32_f16 v[76:79], v[198:201], v[222:225], v[76:79]
	v_mfma_f32_16x16x32_f16 v[68:71], v[190:193], v[230:233], v[68:71]
	v_mfma_f32_16x16x32_f16 v[64:67], v[198:201], v[230:233], v[64:67]
	v_mfma_f32_16x16x32_f16 v[116:119], v[194:197], v[210:213], v[116:119]
	v_mfma_f32_16x16x32_f16 v[108:111], v[202:205], v[210:213], v[108:111]
	v_mfma_f32_16x16x32_f16 v[100:103], v[194:197], v[218:221], v[100:103]
	v_mfma_f32_16x16x32_f16 v[92:95], v[202:205], v[218:221], v[92:95]
	v_mfma_f32_16x16x32_f16 v[84:87], v[194:197], v[226:229], v[84:87]
	v_mfma_f32_16x16x32_f16 v[76:79], v[202:205], v[226:229], v[76:79]
	v_mfma_f32_16x16x32_f16 v[68:71], v[194:197], v[234:237], v[68:71]
	v_mfma_f32_16x16x32_f16 v[64:67], v[202:205], v[234:237], v[64:67]
	s_barrier
	s_add_i32 s90, s90, s74
	v_lshl_add_u64 v[146:147], s[58:59], 0, v[136:137]
	s_mov_b32 m0, s90
	ds_read_b128 v[206:209], v188 offset:16384
	ds_read_b128 v[210:213], v188 offset:17408
	ds_read_b128 v[214:217], v188 offset:18432
	ds_read_b128 v[218:221], v188 offset:19456
	ds_read_b128 v[222:225], v188 offset:20480
	ds_read_b128 v[226:229], v188 offset:21504
	ds_read_b128 v[230:233], v188 offset:22528
	ds_read_b128 v[234:237], v188 offset:23552
	global_load_lds_dwordx4 v[146:147], off
	s_add_i32 m0, s90, 0x2000
	s_add_u32 s90, s58, 0x40000
	v_lshl_add_u64 v[168:169], s[58:59], 0, v[132:133]
	s_addc_u32 s91, s59, 0
	s_add_i32 s31, s31, s74
	global_load_lds_dwordx4 v[168:169], off
	v_lshl_add_u64 v[238:239], s[90:91], 0, v[136:137]
	s_mov_b32 m0, s31
	v_lshl_add_u64 v[240:241], s[62:63], 0, v[134:135]
	global_load_lds_dwordx4 v[238:239], off
	v_lshl_add_u64 v[238:239], s[90:91], 0, v[132:133]
	s_add_i32 m0, s31, 0x2000
	s_nop 0
	global_load_lds_dwordx4 v[238:239], off
	v_lshl_add_u64 v[238:239], s[62:63], 0, v[138:139]
	s_mov_b32 m0, s76
	s_nop 0
	global_load_lds_dwordx4 v[238:239], off
	s_mov_b32 m0, s77
	s_nop 0
	global_load_lds_dwordx4 v[240:241], off
	s_waitcnt vmcnt(8)
	s_waitcnt lgkmcnt(0)
	s_barrier
; #define PG8_STAGE(bufoff, gbase, voff) do { _Pragma("unroll") for (int _i = 0; _i < 2; ++_i) \
;         __builtin_amdgcn_global_load_lds((const unsigned*)((const char*)(gbase) + (voff)[_i]), (PG8_LAS unsigned*)(lds + (bufoff) + ldsw + _i * 8192), 16, 0, 0); } while (0)
; #define PG8_LDA(dst, b, h) do { _Pragma("unroll") for (int m = 0; m < 4; ++m) _Pragma("unroll") for (int k = 0; k < 2; ++k) dst[m][k] = *(const PG8_LAS bf16x8*)(lds + PG8_SA(b, h) + aoff + m * 2048 + k * 1024); } while (0)
; #define PG8_LDB(dst, b, h) do { _Pragma("unroll") for (int n = 0; n < 2; ++n) _Pragma("unroll") for (int k = 0; k < 2; ++k) dst[n][k] = *(const PG8_LAS bf16x8*)(lds + PG8_SB(b, h) + boff + n * 2048 + k * 1024); } while (0)
; #define PG8_WAIT_V(n) asm volatile("s_waitcnt vmcnt(" #n ")" ::: "memory")
; #define PG8_WAIT_L(n) asm volatile("s_waitcnt lgkmcnt(" #n ")" ::: "memory")
; #define PG8_BAR __builtin_amdgcn_s_barrier()
; #define PG8_SCHED __builtin_amdgcn_sched_barrier(0)
; template <class Epi, class Sched, bool ALIGN_EPI = false, bool SP2 = false, bool F16 = false>
; __device__ __forceinline__ void gemm_phase(PG8_LAS unsigned char* lds, const Gemm g, const Sched& S, const Epi& E) {
;     ...
;             PG8_WAIT_V(8); PG8_WAIT_L(0); PG8_BAR; PG8_MMA(1, 0, At, B0); PG8_MMA(1, 1, At, B1); PG8_BAR; PG8_SCHED;
;             PG8_LDB(B0, 1, 0); PG8_LDB(B1, 1, 1); PG8_SCHED; PG8_LDA(At, 1, 0); PG8_STAGE(PG8_SA(0, 1), a2 + hstep, voffA);
;             PG8_WAIT_V(8); PG8_WAIT_L(0); PG8_BAR; PG8_MMA(0, 0, At, B0); PG8_MMA(0, 1, At, B1); PG8_BAR; PG8_SCHED;
;             PG8_LDA(At, 1, 1); PG8_STAGE(PG8_SB(1, 0), b3, voffB); PG8_STAGE(PG8_SB(1, 1), b3 + hstep, voffB); PG8_STAGE(PG8_SA(1, 0), a3, voffA);
	s_waitcnt lgkmcnt(0)
	v_mfma_f32_16x16x32_f16 v[60:63], v[128:131], v[206:209], v[60:63]
	v_mfma_f32_16x16x32_f16 v[56:59], v[160:163], v[206:209], v[56:59]
	v_mfma_f32_16x16x32_f16 v[48:51], v[128:131], v[214:217], v[48:51]
	v_mfma_f32_16x16x32_f16 v[40:43], v[160:163], v[214:217], v[40:43]
	v_mfma_f32_16x16x32_f16 v[32:35], v[128:131], v[222:225], v[32:35]
	v_mfma_f32_16x16x32_f16 v[24:27], v[160:163], v[222:225], v[24:27]
	v_mfma_f32_16x16x32_f16 v[16:19], v[128:131], v[230:233], v[16:19]
	v_mfma_f32_16x16x32_f16 v[8:11], v[160:163], v[230:233], v[8:11]
	v_mfma_f32_16x16x32_f16 v[60:63], v[156:159], v[210:213], v[60:63]
	v_mfma_f32_16x16x32_f16 v[56:59], v[164:167], v[210:213], v[56:59]
	v_mfma_f32_16x16x32_f16 v[48:51], v[156:159], v[218:221], v[48:51]
	v_mfma_f32_16x16x32_f16 v[40:43], v[164:167], v[218:221], v[40:43]
	v_mfma_f32_16x16x32_f16 v[32:35], v[156:159], v[226:229], v[32:35]
	v_mfma_f32_16x16x32_f16 v[24:27], v[164:167], v[226:229], v[24:27]
	v_mfma_f32_16x16x32_f16 v[16:19], v[156:159], v[234:237], v[16:19]
	v_mfma_f32_16x16x32_f16 v[8:11], v[164:167], v[234:237], v[8:11]
	v_mfma_f32_16x16x32_f16 v[52:55], v[190:193], v[206:209], v[52:55]
	v_mfma_f32_16x16x32_f16 v[44:47], v[198:201], v[206:209], v[44:47]
	v_mfma_f32_16x16x32_f16 v[36:39], v[190:193], v[214:217], v[36:39]
	v_mfma_f32_16x16x32_f16 v[28:31], v[198:201], v[214:217], v[28:31]
	v_mfma_f32_16x16x32_f16 v[20:23], v[190:193], v[222:225], v[20:23]
	v_mfma_f32_16x16x32_f16 v[12:15], v[198:201], v[222:225], v[12:15]
	v_mfma_f32_16x16x32_f16 v[4:7], v[190:193], v[230:233], v[4:7]
	v_mfma_f32_16x16x32_f16 v[0:3], v[198:201], v[230:233], v[0:3]
	v_mfma_f32_16x16x32_f16 v[52:55], v[194:197], v[210:213], v[52:55]
	v_mfma_f32_16x16x32_f16 v[44:47], v[202:205], v[210:213], v[44:47]
	v_mfma_f32_16x16x32_f16 v[36:39], v[194:197], v[218:221], v[36:39]
	v_mfma_f32_16x16x32_f16 v[28:31], v[202:205], v[218:221], v[28:31]
	v_mfma_f32_16x16x32_f16 v[20:23], v[194:197], v[226:229], v[20:23]
	v_mfma_f32_16x16x32_f16 v[12:15], v[202:205], v[226:229], v[12:15]
	v_mfma_f32_16x16x32_f16 v[4:7], v[194:197], v[234:237], v[4:7]
	v_mfma_f32_16x16x32_f16 v[0:3], v[202:205], v[234:237], v[0:3]
	s_barrier
	s_add_i32 s31, 0, 0x18000
	v_add_u32_e32 v150, s31, v186
	s_add_i32 s90, 0, 0x1c000
	ds_read_b128 v[128:131], v150
	ds_read_b128 v[156:159], v150 offset:1024
	ds_read_b128 v[160:163], v150 offset:2048
	ds_read_b128 v[164:167], v150 offset:3072
	v_add_u32_e32 v150, s90, v186
	ds_read_b128 v[190:193], v150
	ds_read_b128 v[194:197], v150 offset:1024
	ds_read_b128 v[198:201], v150 offset:2048
	ds_read_b128 v[202:205], v150 offset:3072
	s_add_u32 s62, s62, 0x40000
	s_addc_u32 s63, s63, 0
	s_mov_b32 m0, s78
	v_lshl_add_u64 v[242:243], s[62:63], 0, v[138:139]
	ds_read_b128 v[206:209], v188 offset:32768
	ds_read_b128 v[210:213], v188 offset:33792
	ds_read_b128 v[214:217], v188 offset:34816
	ds_read_b128 v[218:221], v188 offset:35840
	ds_read_b128 v[222:225], v188 offset:36864
	ds_read_b128 v[226:229], v188 offset:37888
	ds_read_b128 v[230:233], v188 offset:38912
	ds_read_b128 v[234:237], v188 offset:39936
	global_load_lds_dwordx4 v[242:243], off
	v_lshl_add_u64 v[242:243], s[62:63], 0, v[134:135]
	s_mov_b32 m0, s79
	s_nop 0
	global_load_lds_dwordx4 v[242:243], off
	s_waitcnt vmcnt(8)
	s_waitcnt lgkmcnt(0)
	s_barrier
	s_waitcnt lgkmcnt(0)
	v_mfma_f32_16x16x32_f16 v[124:127], v[128:131], v[206:209], v[124:127]
	v_mfma_f32_16x16x32_f16 v[120:123], v[160:163], v[206:209], v[120:123]
	v_mfma_f32_16x16x32_f16 v[112:115], v[128:131], v[214:217], v[112:115]
	v_mfma_f32_16x16x32_f16 v[104:107], v[160:163], v[214:217], v[104:107]
	v_mfma_f32_16x16x32_f16 v[96:99], v[128:131], v[222:225], v[96:99]
	v_mfma_f32_16x16x32_f16 v[88:91], v[160:163], v[222:225], v[88:91]
	v_mfma_f32_16x16x32_f16 v[80:83], v[128:131], v[230:233], v[80:83]
	v_mfma_f32_16x16x32_f16 v[72:75], v[160:163], v[230:233], v[72:75]
	v_mfma_f32_16x16x32_f16 v[124:127], v[156:159], v[210:213], v[124:127]
	v_mfma_f32_16x16x32_f16 v[120:123], v[164:167], v[210:213], v[120:123]
	v_mfma_f32_16x16x32_f16 v[112:115], v[156:159], v[218:221], v[112:115]
	v_mfma_f32_16x16x32_f16 v[104:107], v[164:167], v[218:221], v[104:107]
	v_mfma_f32_16x16x32_f16 v[96:99], v[156:159], v[226:229], v[96:99]
	v_mfma_f32_16x16x32_f16 v[88:91], v[164:167], v[226:229], v[88:91]
	v_mfma_f32_16x16x32_f16 v[80:83], v[156:159], v[234:237], v[80:83]
	v_mfma_f32_16x16x32_f16 v[72:75], v[164:167], v[234:237], v[72:75]
	v_mfma_f32_16x16x32_f16 v[116:119], v[190:193], v[206:209], v[116:119]
	v_mfma_f32_16x16x32_f16 v[108:111], v[198:201], v[206:209], v[108:111]
	v_mfma_f32_16x16x32_f16 v[100:103], v[190:193], v[214:217], v[100:103]
	v_mfma_f32_16x16x32_f16 v[92:95], v[198:201], v[214:217], v[92:95]
	v_mfma_f32_16x16x32_f16 v[84:87], v[190:193], v[222:225], v[84:87]
	v_mfma_f32_16x16x32_f16 v[76:79], v[198:201], v[222:225], v[76:79]
	v_mfma_f32_16x16x32_f16 v[68:71], v[190:193], v[230:233], v[68:71]
	v_mfma_f32_16x16x32_f16 v[64:67], v[198:201], v[230:233], v[64:67]
	v_mfma_f32_16x16x32_f16 v[116:119], v[194:197], v[210:213], v[116:119]
	v_mfma_f32_16x16x32_f16 v[108:111], v[202:205], v[210:213], v[108:111]
	v_mfma_f32_16x16x32_f16 v[100:103], v[194:197], v[218:221], v[100:103]
	v_mfma_f32_16x16x32_f16 v[92:95], v[202:205], v[218:221], v[92:95]
	v_mfma_f32_16x16x32_f16 v[84:87], v[194:197], v[226:229], v[84:87]
	v_mfma_f32_16x16x32_f16 v[76:79], v[202:205], v[226:229], v[76:79]
	v_mfma_f32_16x16x32_f16 v[68:71], v[194:197], v[234:237], v[68:71]
	v_mfma_f32_16x16x32_f16 v[64:67], v[202:205], v[234:237], v[64:67]
	s_barrier
; #define PG8_STAGE(bufoff, gbase, voff) do { _Pragma("unroll") for (int _i = 0; _i < 2; ++_i) \
;         __builtin_amdgcn_global_load_lds((const unsigned*)((const char*)(gbase) + (voff)[_i]), (PG8_LAS unsigned*)(lds + (bufoff) + ldsw + _i * 8192), 16, 0, 0); } while (0)
; #define PG8_LDA(dst, b, h) do { _Pragma("unroll") for (int m = 0; m < 4; ++m) _Pragma("unroll") for (int k = 0; k < 2; ++k) dst[m][k] = *(const PG8_LAS bf16x8*)(lds + PG8_SA(b, h) + aoff + m * 2048 + k * 1024); } while (0)
; #define PG8_WAIT_V(n) asm volatile("s_waitcnt vmcnt(" #n ")" ::: "memory")
; #define PG8_WAIT_L(n) asm volatile("s_waitcnt lgkmcnt(" #n ")" ::: "memory")
; #define PG8_BAR __builtin_amdgcn_s_barrier()
; #define PG8_SCHED __builtin_amdgcn_sched_barrier(0)
; template <class Epi, class Sched, bool ALIGN_EPI = false, bool SP2 = false, bool F16 = false>
; __device__ __forceinline__ void gemm_phase(PG8_LAS unsigned char* lds, const Gemm g, const Sched& S, const Epi& E) {
;     ...
;         for (int t = 0; t < nt; t += 2) {
;     ...
;             PG8_LDA(At, 1, 1); PG8_STAGE(PG8_SB(1, 0), b3, voffB); PG8_STAGE(PG8_SB(1, 1), b3 + hstep, voffB); PG8_STAGE(PG8_SA(1, 0), a3, voffA);
;             PG8_WAIT_V(8); PG8_WAIT_L(0); PG8_BAR; PG8_MMA(1, 0, At, B0); PG8_MMA(1, 1, At, B1); PG8_BAR; PG8_SCHED;
	s_add_i32 s31, s31, s74
	v_lshl_add_u64 v[146:147], v[146:147], 0, s[22:23]
	s_mov_b32 m0, s31
	ds_read_b128 v[206:209], v188 offset:49152
	ds_read_b128 v[210:213], v188 offset:50176
	ds_read_b128 v[214:217], v188 offset:51200
	ds_read_b128 v[218:221], v188 offset:52224
	ds_read_b128 v[222:225], v188 offset:53248
	ds_read_b128 v[226:229], v188 offset:54272
	ds_read_b128 v[230:233], v188 offset:55296
	ds_read_b128 v[234:237], v188 offset:56320
	global_load_lds_dwordx4 v[146:147], off
	s_add_i32 m0, s31, 0x2000
	s_add_u32 s58, s58, 0x40080
	v_lshl_add_u64 v[146:147], v[168:169], 0, s[22:23]
	s_addc_u32 s59, s59, 0
	s_add_i32 s31, s90, s74
	global_load_lds_dwordx4 v[146:147], off
	v_lshl_add_u64 v[146:147], s[58:59], 0, v[136:137]
	s_mov_b32 m0, s31
	s_nop 0
	global_load_lds_dwordx4 v[146:147], off
	v_lshl_add_u64 v[146:147], s[58:59], 0, v[132:133]
	s_add_i32 m0, s31, 0x2000
	s_nop 0
	global_load_lds_dwordx4 v[146:147], off
	v_lshl_add_u64 v[146:147], v[238:239], 0, s[22:23]
	s_mov_b32 m0, s80
	s_nop 0
	global_load_lds_dwordx4 v[146:147], off
	v_lshl_add_u64 v[146:147], v[240:241], 0, s[22:23]
	s_mov_b32 m0, s81
	s_nop 0
	global_load_lds_dwordx4 v[146:147], off
	s_waitcnt vmcnt(8)
	s_waitcnt lgkmcnt(0)
	s_barrier
	s_waitcnt lgkmcnt(0)
	v_mfma_f32_16x16x32_f16 v[60:63], v[128:131], v[206:209], v[60:63]
	v_mfma_f32_16x16x32_f16 v[56:59], v[160:163], v[206:209], v[56:59]
	v_mfma_f32_16x16x32_f16 v[48:51], v[128:131], v[214:217], v[48:51]
	v_mfma_f32_16x16x32_f16 v[40:43], v[160:163], v[214:217], v[40:43]
	v_mfma_f32_16x16x32_f16 v[32:35], v[128:131], v[222:225], v[32:35]
	v_mfma_f32_16x16x32_f16 v[24:27], v[160:163], v[222:225], v[24:27]
	v_mfma_f32_16x16x32_f16 v[16:19], v[128:131], v[230:233], v[16:19]
	v_mfma_f32_16x16x32_f16 v[8:11], v[160:163], v[230:233], v[8:11]
	v_mfma_f32_16x16x32_f16 v[60:63], v[156:159], v[210:213], v[60:63]
	v_mfma_f32_16x16x32_f16 v[56:59], v[164:167], v[210:213], v[56:59]
	v_mfma_f32_16x16x32_f16 v[48:51], v[156:159], v[218:221], v[48:51]
	v_mfma_f32_16x16x32_f16 v[40:43], v[164:167], v[218:221], v[40:43]
	v_mfma_f32_16x16x32_f16 v[32:35], v[156:159], v[226:229], v[32:35]
	v_mfma_f32_16x16x32_f16 v[24:27], v[164:167], v[226:229], v[24:27]
	v_mfma_f32_16x16x32_f16 v[16:19], v[156:159], v[234:237], v[16:19]
	v_mfma_f32_16x16x32_f16 v[8:11], v[164:167], v[234:237], v[8:11]
	v_mfma_f32_16x16x32_f16 v[52:55], v[190:193], v[206:209], v[52:55]
	v_mfma_f32_16x16x32_f16 v[44:47], v[198:201], v[206:209], v[44:47]
	v_mfma_f32_16x16x32_f16 v[36:39], v[190:193], v[214:217], v[36:39]
	v_mfma_f32_16x16x32_f16 v[28:31], v[198:201], v[214:217], v[28:31]
	v_mfma_f32_16x16x32_f16 v[20:23], v[190:193], v[222:225], v[20:23]
	v_mfma_f32_16x16x32_f16 v[12:15], v[198:201], v[222:225], v[12:15]
	v_mfma_f32_16x16x32_f16 v[4:7], v[190:193], v[230:233], v[4:7]
	v_mfma_f32_16x16x32_f16 v[0:3], v[198:201], v[230:233], v[0:3]
	v_mfma_f32_16x16x32_f16 v[52:55], v[194:197], v[210:213], v[52:55]
	v_mfma_f32_16x16x32_f16 v[44:47], v[202:205], v[210:213], v[44:47]
	v_mfma_f32_16x16x32_f16 v[36:39], v[194:197], v[218:221], v[36:39]
	v_mfma_f32_16x16x32_f16 v[28:31], v[202:205], v[218:221], v[28:31]
	v_mfma_f32_16x16x32_f16 v[20:23], v[194:197], v[226:229], v[20:23]
	v_mfma_f32_16x16x32_f16 v[12:15], v[202:205], v[226:229], v[12:15]
	v_mfma_f32_16x16x32_f16 v[4:7], v[194:197], v[234:237], v[4:7]
	v_mfma_f32_16x16x32_f16 v[0:3], v[202:205], v[234:237], v[0:3]
	s_barrier
	s_add_i32 s30, s30, 2
	s_add_u32 s56, s56, 0x100
	s_addc_u32 s57, s57, 0
	s_add_u32 vcc_lo, vcc_lo, 0x100
	s_addc_u32 vcc_hi, vcc_hi, 0
	s_cmp_gt_u32 s30, 13
	s_cbranch_scc0 .LBB0_102
	s_and_b64 vcc, exec, s[6:7]
	s_cbranch_vccz .LBB0_105
	s_barrier

; #define PG8_STAGE(bufoff, gbase, voff) do { _Pragma("unroll") for (int _i = 0; _i < 2; ++_i) \
;         __builtin_amdgcn_global_load_lds((const unsigned*)((const char*)(gbase) + (voff)[_i]), (PG8_LAS unsigned*)(lds + (bufoff) + ldsw + _i * 8192), 16, 0, 0); } while (0)
; #define PG8_LDA(dst, b, h) do { _Pragma("unroll") for (int m = 0; m < 4; ++m) _Pragma("unroll") for (int k = 0; k < 2; ++k) dst[m][k] = *(const PG8_LAS bf16x8*)(lds + PG8_SA(b, h) + aoff + m * 2048 + k * 1024); } while (0)
; #define PG8_LDB(dst, b, h) do { _Pragma("unroll") for (int n = 0; n < 2; ++n) _Pragma("unroll") for (int k = 0; k < 2; ++k) dst[n][k] = *(const PG8_LAS bf16x8*)(lds + PG8_SB(b, h) + boff + n * 2048 + k * 1024); } while (0)
; #define PG8_WAIT_V(n) asm volatile("s_waitcnt vmcnt(" #n ")" ::: "memory")
; #define PG8_WAIT_L(n) asm volatile("s_waitcnt lgkmcnt(" #n ")" ::: "memory")
; #define PG8_BAR __builtin_amdgcn_s_barrier()
; #define PG8_SCHED __builtin_amdgcn_sched_barrier(0)
; template <class Epi, class Sched, bool ALIGN_EPI = false, bool SP2 = false, bool F16 = false>
; __device__ __forceinline__ void gemm_phase(PG8_LAS unsigned char* lds, const Gemm g, const Sched& S, const Epi& E) {
;     ...
;             if constexpr (SP2) {
;             PG8_LDB(B0, 0, 0); PG8_LDB(B1, 0, 1); PG8_SCHED; PG8_LDA(At, 0, 0); PG8_STAGE(PG8_SA(1, 1), a1 + hstep, voffA);
;             PG8_WAIT_V(8); PG8_WAIT_L(0); PG8_BAR; PG8_MMA(0, 0, At, B0); PG8_MMA(0, 1, At, B1); PG8_BAR; PG8_SCHED;
;             PG8_LDA(At, 0, 1); PG8_STAGE(PG8_SB(0, 0), b2, voffB); PG8_STAGE(PG8_SB(0, 1), b2 + hstep, voffB); PG8_STAGE(PG8_SA(0, 0), a2, voffA);
;             PG8_WAIT_V(8); PG8_WAIT_L(0); PG8_BAR; PG8_MMA(1, 0, At, B0); PG8_MMA(1, 1, At, B1); PG8_BAR; PG8_SCHED;
.LBB0_136:
	s_add_u32 s31, s48, 0xfffc0080
	s_addc_u32 s50, s49, -1
	s_add_i32 s77, 0, 0x10000
	s_cmp_eq_u32 s30, 12
	s_cselect_b32 s53, s13, s50
	s_cselect_b32 s52, s72, s31
	v_add_u32_e32 v168, s77, v162
	s_cselect_b32 s51, s9, s76
	s_cselect_b32 s50, s74, s75
	s_add_i32 s31, 0, 0x14000
	ds_read_b128 v[164:167], v168
	ds_read_b128 v[186:189], v168 offset:1024
	ds_read_b128 v[190:193], v168 offset:2048
	ds_read_b128 v[194:197], v168 offset:3072
	v_add_u32_e32 v168, s31, v162
	ds_read_b128 v[198:201], v168
	ds_read_b128 v[202:205], v168 offset:1024
	ds_read_b128 v[206:209], v168 offset:2048
	ds_read_b128 v[210:213], v168 offset:3072
	v_lshl_add_u64 v[168:169], s[48:49], 0, v[136:137]
	s_add_i32 m0, s57, 0xc000
	ds_read_b128 v[214:217], v163
	ds_read_b128 v[218:221], v163 offset:1024
	ds_read_b128 v[222:225], v163 offset:2048
	ds_read_b128 v[226:229], v163 offset:3072
	ds_read_b128 v[230:233], v163 offset:4096
	ds_read_b128 v[234:237], v163 offset:5120
	ds_read_b128 v[238:241], v163 offset:6144
	ds_read_b128 v[242:245], v163 offset:7168
	global_load_lds_dwordx4 v[168:169], off
	v_lshl_add_u64 v[168:169], s[48:49], 0, v[138:139]
	s_add_i32 m0, s57, 0xe000
	s_nop 0
	global_load_lds_dwordx4 v[168:169], off
	s_waitcnt vmcnt(8)
	s_waitcnt lgkmcnt(0)
	s_barrier
	s_waitcnt lgkmcnt(0)
	v_mfma_f32_16x16x32_f16 v[124:127], v[164:167], v[214:217], v[124:127]
	v_mfma_f32_16x16x32_f16 v[120:123], v[190:193], v[214:217], v[120:123]
	v_mfma_f32_16x16x32_f16 v[116:119], v[164:167], v[222:225], v[116:119]
	v_mfma_f32_16x16x32_f16 v[112:115], v[190:193], v[222:225], v[112:115]
	v_mfma_f32_16x16x32_f16 v[108:111], v[164:167], v[230:233], v[108:111]
	v_mfma_f32_16x16x32_f16 v[104:107], v[190:193], v[230:233], v[104:107]
	v_mfma_f32_16x16x32_f16 v[100:103], v[164:167], v[238:241], v[100:103]
	v_mfma_f32_16x16x32_f16 v[96:99], v[190:193], v[238:241], v[96:99]
	v_mfma_f32_16x16x32_f16 v[124:127], v[186:189], v[218:221], v[124:127]
	v_mfma_f32_16x16x32_f16 v[120:123], v[194:197], v[218:221], v[120:123]
	v_mfma_f32_16x16x32_f16 v[116:119], v[186:189], v[226:229], v[116:119]
	v_mfma_f32_16x16x32_f16 v[112:115], v[194:197], v[226:229], v[112:115]
	v_mfma_f32_16x16x32_f16 v[108:111], v[186:189], v[234:237], v[108:111]
	v_mfma_f32_16x16x32_f16 v[104:107], v[194:197], v[234:237], v[104:107]
	v_mfma_f32_16x16x32_f16 v[100:103], v[186:189], v[242:245], v[100:103]
	v_mfma_f32_16x16x32_f16 v[96:99], v[194:197], v[242:245], v[96:99]
	v_mfma_f32_16x16x32_f16 v[76:79], v[198:201], v[214:217], v[76:79]
	v_mfma_f32_16x16x32_f16 v[68:71], v[206:209], v[214:217], v[68:71]
	v_mfma_f32_16x16x32_f16 v[60:63], v[198:201], v[222:225], v[60:63]
	v_mfma_f32_16x16x32_f16 v[52:55], v[206:209], v[222:225], v[52:55]
	v_mfma_f32_16x16x32_f16 v[44:47], v[198:201], v[230:233], v[44:47]
	v_mfma_f32_16x16x32_f16 v[40:43], v[206:209], v[230:233], v[40:43]
	v_mfma_f32_16x16x32_f16 v[36:39], v[198:201], v[238:241], v[36:39]
	v_mfma_f32_16x16x32_f16 v[32:35], v[206:209], v[238:241], v[32:35]
	v_mfma_f32_16x16x32_f16 v[76:79], v[202:205], v[218:221], v[76:79]
	v_mfma_f32_16x16x32_f16 v[68:71], v[210:213], v[218:221], v[68:71]
	v_mfma_f32_16x16x32_f16 v[60:63], v[202:205], v[226:229], v[60:63]
	v_mfma_f32_16x16x32_f16 v[52:55], v[210:213], v[226:229], v[52:55]
	v_mfma_f32_16x16x32_f16 v[44:47], v[202:205], v[234:237], v[44:47]
	v_mfma_f32_16x16x32_f16 v[40:43], v[210:213], v[234:237], v[40:43]
	v_mfma_f32_16x16x32_f16 v[36:39], v[202:205], v[242:245], v[36:39]
	v_mfma_f32_16x16x32_f16 v[32:35], v[210:213], v[242:245], v[32:35]
	s_barrier
	s_add_i32 s77, s77, s56
	v_lshl_add_u64 v[168:169], s[50:51], 0, v[150:151]
	s_mov_b32 m0, s77
	ds_read_b128 v[214:217], v163 offset:16384
	ds_read_b128 v[218:221], v163 offset:17408
	ds_read_b128 v[222:225], v163 offset:18432
	ds_read_b128 v[226:229], v163 offset:19456
	ds_read_b128 v[230:233], v163 offset:20480
	ds_read_b128 v[234:237], v163 offset:21504
	ds_read_b128 v[238:241], v163 offset:22528
	ds_read_b128 v[242:245], v163 offset:23552
	global_load_lds_dwordx4 v[168:169], off
	s_add_i32 m0, s77, 0x2000
	s_add_u32 s78, s50, 0x40000
	v_lshl_add_u64 v[246:247], s[50:51], 0, v[132:133]
	s_addc_u32 s79, s51, 0
	s_add_i32 s31, s31, s56
	global_load_lds_dwordx4 v[246:247], off
	v_lshl_add_u64 v[248:249], s[78:79], 0, v[150:151]
	s_mov_b32 m0, s31
	v_lshl_add_u64 v[250:251], s[52:53], 0, v[130:131]
	global_load_lds_dwordx4 v[248:249], off
	v_lshl_add_u64 v[248:249], s[78:79], 0, v[132:133]
	s_add_i32 m0, s31, 0x2000
	s_nop 0
	global_load_lds_dwordx4 v[248:249], off
	v_lshl_add_u64 v[248:249], s[52:53], 0, v[128:129]
	s_mov_b32 m0, s57
	s_nop 0
	global_load_lds_dwordx4 v[248:249], off
	s_mov_b32 m0, s58
	s_nop 0
	global_load_lds_dwordx4 v[250:251], off
	s_waitcnt vmcnt(8)
	s_waitcnt lgkmcnt(0)
	s_barrier
; #define PG8_STAGE(bufoff, gbase, voff) do { _Pragma("unroll") for (int _i = 0; _i < 2; ++_i) \
;         __builtin_amdgcn_global_load_lds((const unsigned*)((const char*)(gbase) + (voff)[_i]), (PG8_LAS unsigned*)(lds + (bufoff) + ldsw + _i * 8192), 16, 0, 0); } while (0)
; #define PG8_LDA(dst, b, h) do { _Pragma("unroll") for (int m = 0; m < 4; ++m) _Pragma("unroll") for (int k = 0; k < 2; ++k) dst[m][k] = *(const PG8_LAS bf16x8*)(lds + PG8_SA(b, h) + aoff + m * 2048 + k * 1024); } while (0)
; #define PG8_LDB(dst, b, h) do { _Pragma("unroll") for (int n = 0; n < 2; ++n) _Pragma("unroll") for (int k = 0; k < 2; ++k) dst[n][k] = *(const PG8_LAS bf16x8*)(lds + PG8_SB(b, h) + boff + n * 2048 + k * 1024); } while (0)
; #define PG8_WAIT_V(n) asm volatile("s_waitcnt vmcnt(" #n ")" ::: "memory")
; #define PG8_WAIT_L(n) asm volatile("s_waitcnt lgkmcnt(" #n ")" ::: "memory")
; #define PG8_BAR __builtin_amdgcn_s_barrier()
; #define PG8_SCHED __builtin_amdgcn_sched_barrier(0)
; template <class Epi, class Sched, bool ALIGN_EPI = false, bool SP2 = false, bool F16 = false>
; __device__ __forceinline__ void gemm_phase(PG8_LAS unsigned char* lds, const Gemm g, const Sched& S, const Epi& E) {
;     ...
;             PG8_WAIT_V(8); PG8_WAIT_L(0); PG8_BAR; PG8_MMA(1, 0, At, B0); PG8_MMA(1, 1, At, B1); PG8_BAR; PG8_SCHED;
;             PG8_LDB(B0, 1, 0); PG8_LDB(B1, 1, 1); PG8_SCHED; PG8_LDA(At, 1, 0); PG8_STAGE(PG8_SA(0, 1), a2 + hstep, voffA);
;             PG8_WAIT_V(8); PG8_WAIT_L(0); PG8_BAR; PG8_MMA(0, 0, At, B0); PG8_MMA(0, 1, At, B1); PG8_BAR; PG8_SCHED;
;             PG8_LDA(At, 1, 1); PG8_STAGE(PG8_SB(1, 0), b3, voffB); PG8_STAGE(PG8_SB(1, 1), b3 + hstep, voffB); PG8_STAGE(PG8_SA(1, 0), a3, voffA);
	s_waitcnt lgkmcnt(0)
	v_mfma_f32_16x16x32_f16 v[92:95], v[164:167], v[214:217], v[92:95]
	v_mfma_f32_16x16x32_f16 v[88:91], v[190:193], v[214:217], v[88:91]
	v_mfma_f32_16x16x32_f16 v[84:87], v[164:167], v[222:225], v[84:87]
	v_mfma_f32_16x16x32_f16 v[80:83], v[190:193], v[222:225], v[80:83]
	v_mfma_f32_16x16x32_f16 v[72:75], v[164:167], v[230:233], v[72:75]
	v_mfma_f32_16x16x32_f16 v[64:67], v[190:193], v[230:233], v[64:67]
	v_mfma_f32_16x16x32_f16 v[56:59], v[164:167], v[238:241], v[56:59]
	v_mfma_f32_16x16x32_f16 v[48:51], v[190:193], v[238:241], v[48:51]
	v_mfma_f32_16x16x32_f16 v[92:95], v[186:189], v[218:221], v[92:95]
	v_mfma_f32_16x16x32_f16 v[88:91], v[194:197], v[218:221], v[88:91]
	v_mfma_f32_16x16x32_f16 v[84:87], v[186:189], v[226:229], v[84:87]
	v_mfma_f32_16x16x32_f16 v[80:83], v[194:197], v[226:229], v[80:83]
	v_mfma_f32_16x16x32_f16 v[72:75], v[186:189], v[234:237], v[72:75]
	v_mfma_f32_16x16x32_f16 v[64:67], v[194:197], v[234:237], v[64:67]
	v_mfma_f32_16x16x32_f16 v[56:59], v[186:189], v[242:245], v[56:59]
	v_mfma_f32_16x16x32_f16 v[48:51], v[194:197], v[242:245], v[48:51]
	v_mfma_f32_16x16x32_f16 v[28:31], v[198:201], v[214:217], v[28:31]
	v_mfma_f32_16x16x32_f16 v[24:27], v[206:209], v[214:217], v[24:27]
	v_mfma_f32_16x16x32_f16 v[20:23], v[198:201], v[222:225], v[20:23]
	v_mfma_f32_16x16x32_f16 v[16:19], v[206:209], v[222:225], v[16:19]
	v_mfma_f32_16x16x32_f16 v[12:15], v[198:201], v[230:233], v[12:15]
	v_mfma_f32_16x16x32_f16 v[8:11], v[206:209], v[230:233], v[8:11]
	v_mfma_f32_16x16x32_f16 v[4:7], v[198:201], v[238:241], v[4:7]
	v_mfma_f32_16x16x32_f16 v[0:3], v[206:209], v[238:241], v[0:3]
	v_mfma_f32_16x16x32_f16 v[28:31], v[202:205], v[218:221], v[28:31]
	v_mfma_f32_16x16x32_f16 v[24:27], v[210:213], v[218:221], v[24:27]
	v_mfma_f32_16x16x32_f16 v[20:23], v[202:205], v[226:229], v[20:23]
	v_mfma_f32_16x16x32_f16 v[16:19], v[210:213], v[226:229], v[16:19]
	v_mfma_f32_16x16x32_f16 v[12:15], v[202:205], v[234:237], v[12:15]
	v_mfma_f32_16x16x32_f16 v[8:11], v[210:213], v[234:237], v[8:11]
	v_mfma_f32_16x16x32_f16 v[4:7], v[202:205], v[242:245], v[4:7]
	v_mfma_f32_16x16x32_f16 v[0:3], v[210:213], v[242:245], v[0:3]
	s_barrier
	s_add_i32 s31, 0, 0x18000
	v_add_u32_e32 v170, s31, v162
	s_add_i32 s77, 0, 0x1c000
	ds_read_b128 v[164:167], v170
	ds_read_b128 v[186:189], v170 offset:1024
	ds_read_b128 v[190:193], v170 offset:2048
	ds_read_b128 v[194:197], v170 offset:3072
	v_add_u32_e32 v170, s77, v162
	ds_read_b128 v[198:201], v170
	ds_read_b128 v[202:205], v170 offset:1024
	ds_read_b128 v[206:209], v170 offset:2048
	ds_read_b128 v[210:213], v170 offset:3072
	s_add_u32 s52, s52, 0x40000
	s_addc_u32 s53, s53, 0
	s_mov_b32 m0, s59
	v_lshl_add_u64 v[252:253], s[52:53], 0, v[128:129]
	ds_read_b128 v[214:217], v163 offset:32768
	ds_read_b128 v[218:221], v163 offset:33792
	ds_read_b128 v[222:225], v163 offset:34816
	ds_read_b128 v[226:229], v163 offset:35840
	ds_read_b128 v[230:233], v163 offset:36864
	ds_read_b128 v[234:237], v163 offset:37888
	ds_read_b128 v[238:241], v163 offset:38912
	ds_read_b128 v[242:245], v163 offset:39936
	global_load_lds_dwordx4 v[252:253], off
	v_lshl_add_u64 v[252:253], s[52:53], 0, v[130:131]
	s_mov_b32 m0, s60
	s_nop 0
	global_load_lds_dwordx4 v[252:253], off
	s_waitcnt vmcnt(8)
	s_waitcnt lgkmcnt(0)
	s_barrier
	s_waitcnt lgkmcnt(0)
	v_mfma_f32_16x16x32_f16 v[124:127], v[164:167], v[214:217], v[124:127]
	v_mfma_f32_16x16x32_f16 v[120:123], v[190:193], v[214:217], v[120:123]
	v_mfma_f32_16x16x32_f16 v[116:119], v[164:167], v[222:225], v[116:119]
	v_mfma_f32_16x16x32_f16 v[112:115], v[190:193], v[222:225], v[112:115]
	v_mfma_f32_16x16x32_f16 v[108:111], v[164:167], v[230:233], v[108:111]
	v_mfma_f32_16x16x32_f16 v[104:107], v[190:193], v[230:233], v[104:107]
	v_mfma_f32_16x16x32_f16 v[100:103], v[164:167], v[238:241], v[100:103]
	v_mfma_f32_16x16x32_f16 v[96:99], v[190:193], v[238:241], v[96:99]
	v_mfma_f32_16x16x32_f16 v[124:127], v[186:189], v[218:221], v[124:127]
	v_mfma_f32_16x16x32_f16 v[120:123], v[194:197], v[218:221], v[120:123]
	v_mfma_f32_16x16x32_f16 v[116:119], v[186:189], v[226:229], v[116:119]
	v_mfma_f32_16x16x32_f16 v[112:115], v[194:197], v[226:229], v[112:115]
	v_mfma_f32_16x16x32_f16 v[108:111], v[186:189], v[234:237], v[108:111]
	v_mfma_f32_16x16x32_f16 v[104:107], v[194:197], v[234:237], v[104:107]
	v_mfma_f32_16x16x32_f16 v[100:103], v[186:189], v[242:245], v[100:103]
	v_mfma_f32_16x16x32_f16 v[96:99], v[194:197], v[242:245], v[96:99]
	v_mfma_f32_16x16x32_f16 v[76:79], v[198:201], v[214:217], v[76:79]
	v_mfma_f32_16x16x32_f16 v[68:71], v[206:209], v[214:217], v[68:71]
	v_mfma_f32_16x16x32_f16 v[60:63], v[198:201], v[222:225], v[60:63]
	v_mfma_f32_16x16x32_f16 v[52:55], v[206:209], v[222:225], v[52:55]
	v_mfma_f32_16x16x32_f16 v[44:47], v[198:201], v[230:233], v[44:47]
	v_mfma_f32_16x16x32_f16 v[40:43], v[206:209], v[230:233], v[40:43]
	v_mfma_f32_16x16x32_f16 v[36:39], v[198:201], v[238:241], v[36:39]
	v_mfma_f32_16x16x32_f16 v[32:35], v[206:209], v[238:241], v[32:35]
	v_mfma_f32_16x16x32_f16 v[76:79], v[202:205], v[218:221], v[76:79]
	v_mfma_f32_16x16x32_f16 v[68:71], v[210:213], v[218:221], v[68:71]
	v_mfma_f32_16x16x32_f16 v[60:63], v[202:205], v[226:229], v[60:63]
	v_mfma_f32_16x16x32_f16 v[52:55], v[210:213], v[226:229], v[52:55]
	v_mfma_f32_16x16x32_f16 v[44:47], v[202:205], v[234:237], v[44:47]
	v_mfma_f32_16x16x32_f16 v[40:43], v[210:213], v[234:237], v[40:43]
	v_mfma_f32_16x16x32_f16 v[36:39], v[202:205], v[242:245], v[36:39]
	v_mfma_f32_16x16x32_f16 v[32:35], v[210:213], v[242:245], v[32:35]
	s_barrier
; #define PG8_STAGE(bufoff, gbase, voff) do { _Pragma("unroll") for (int _i = 0; _i < 2; ++_i) \
;         __builtin_amdgcn_global_load_lds((const unsigned*)((const char*)(gbase) + (voff)[_i]), (PG8_LAS unsigned*)(lds + (bufoff) + ldsw + _i * 8192), 16, 0, 0); } while (0)
; #define PG8_LDA(dst, b, h) do { _Pragma("unroll") for (int m = 0; m < 4; ++m) _Pragma("unroll") for (int k = 0; k < 2; ++k) dst[m][k] = *(const PG8_LAS bf16x8*)(lds + PG8_SA(b, h) + aoff + m * 2048 + k * 1024); } while (0)
; #define PG8_WAIT_V(n) asm volatile("s_waitcnt vmcnt(" #n ")" ::: "memory")
; #define PG8_WAIT_L(n) asm volatile("s_waitcnt lgkmcnt(" #n ")" ::: "memory")
; #define PG8_BAR __builtin_amdgcn_s_barrier()
; #define PG8_SCHED __builtin_amdgcn_sched_barrier(0)
; template <class Epi, class Sched, bool ALIGN_EPI = false, bool SP2 = false, bool F16 = false>
; __device__ __forceinline__ void gemm_phase(PG8_LAS unsigned char* lds, const Gemm g, const Sched& S, const Epi& E) {
;     ...
;         for (int t = 0; t < nt; t += 2) {
;     ...
;             PG8_LDA(At, 1, 1); PG8_STAGE(PG8_SB(1, 0), b3, voffB); PG8_STAGE(PG8_SB(1, 1), b3 + hstep, voffB); PG8_STAGE(PG8_SA(1, 0), a3, voffA);
;             PG8_WAIT_V(8); PG8_WAIT_L(0); PG8_BAR; PG8_MMA(1, 0, At, B0); PG8_MMA(1, 1, At, B1); PG8_BAR; PG8_SCHED;
	s_add_i32 s31, s31, s56
	v_lshl_add_u64 v[168:169], v[168:169], 0, s[22:23]
	s_mov_b32 m0, s31
	ds_read_b128 v[214:217], v163 offset:49152
	ds_read_b128 v[218:221], v163 offset:50176
	ds_read_b128 v[222:225], v163 offset:51200
	ds_read_b128 v[226:229], v163 offset:52224
	ds_read_b128 v[230:233], v163 offset:53248
	ds_read_b128 v[234:237], v163 offset:54272
	ds_read_b128 v[238:241], v163 offset:55296
	ds_read_b128 v[242:245], v163 offset:56320
	global_load_lds_dwordx4 v[168:169], off
	s_add_i32 m0, s31, 0x2000
	s_add_u32 s50, s50, 0x40080
	v_lshl_add_u64 v[168:169], v[246:247], 0, s[22:23]
	s_addc_u32 s51, s51, 0
	s_add_i32 s31, s77, s56
	global_load_lds_dwordx4 v[168:169], off
	v_lshl_add_u64 v[168:169], s[50:51], 0, v[150:151]
	s_mov_b32 m0, s31
	s_nop 0
	global_load_lds_dwordx4 v[168:169], off
	v_lshl_add_u64 v[168:169], s[50:51], 0, v[132:133]
	s_add_i32 m0, s31, 0x2000
	s_nop 0
	global_load_lds_dwordx4 v[168:169], off
	v_lshl_add_u64 v[168:169], v[248:249], 0, s[22:23]
	s_mov_b32 m0, s62
	s_nop 0
	global_load_lds_dwordx4 v[168:169], off
	v_lshl_add_u64 v[168:169], v[250:251], 0, s[22:23]
	s_mov_b32 m0, s63
	s_nop 0
	global_load_lds_dwordx4 v[168:169], off
	s_waitcnt vmcnt(8)
	s_waitcnt lgkmcnt(0)
	s_barrier
	s_waitcnt lgkmcnt(0)
	v_mfma_f32_16x16x32_f16 v[92:95], v[164:167], v[214:217], v[92:95]
	v_mfma_f32_16x16x32_f16 v[88:91], v[190:193], v[214:217], v[88:91]
	v_mfma_f32_16x16x32_f16 v[84:87], v[164:167], v[222:225], v[84:87]
	v_mfma_f32_16x16x32_f16 v[80:83], v[190:193], v[222:225], v[80:83]
	v_mfma_f32_16x16x32_f16 v[72:75], v[164:167], v[230:233], v[72:75]
	v_mfma_f32_16x16x32_f16 v[64:67], v[190:193], v[230:233], v[64:67]
	v_mfma_f32_16x16x32_f16 v[56:59], v[164:167], v[238:241], v[56:59]
	v_mfma_f32_16x16x32_f16 v[48:51], v[190:193], v[238:241], v[48:51]
	v_mfma_f32_16x16x32_f16 v[92:95], v[186:189], v[218:221], v[92:95]
	v_mfma_f32_16x16x32_f16 v[88:91], v[194:197], v[218:221], v[88:91]
	v_mfma_f32_16x16x32_f16 v[84:87], v[186:189], v[226:229], v[84:87]
	v_mfma_f32_16x16x32_f16 v[80:83], v[194:197], v[226:229], v[80:83]
	v_mfma_f32_16x16x32_f16 v[72:75], v[186:189], v[234:237], v[72:75]
	v_mfma_f32_16x16x32_f16 v[64:67], v[194:197], v[234:237], v[64:67]
	v_mfma_f32_16x16x32_f16 v[56:59], v[186:189], v[242:245], v[56:59]
	v_mfma_f32_16x16x32_f16 v[48:51], v[194:197], v[242:245], v[48:51]
	v_mfma_f32_16x16x32_f16 v[28:31], v[198:201], v[214:217], v[28:31]
	v_mfma_f32_16x16x32_f16 v[24:27], v[206:209], v[214:217], v[24:27]
	v_mfma_f32_16x16x32_f16 v[20:23], v[198:201], v[222:225], v[20:23]
	v_mfma_f32_16x16x32_f16 v[16:19], v[206:209], v[222:225], v[16:19]
	v_mfma_f32_16x16x32_f16 v[12:15], v[198:201], v[230:233], v[12:15]
	v_mfma_f32_16x16x32_f16 v[8:11], v[206:209], v[230:233], v[8:11]
	v_mfma_f32_16x16x32_f16 v[4:7], v[198:201], v[238:241], v[4:7]
	v_mfma_f32_16x16x32_f16 v[0:3], v[206:209], v[238:241], v[0:3]
	v_mfma_f32_16x16x32_f16 v[28:31], v[202:205], v[218:221], v[28:31]
	v_mfma_f32_16x16x32_f16 v[24:27], v[210:213], v[218:221], v[24:27]
	v_mfma_f32_16x16x32_f16 v[20:23], v[202:205], v[226:229], v[20:23]
	v_mfma_f32_16x16x32_f16 v[16:19], v[210:213], v[226:229], v[16:19]
	v_mfma_f32_16x16x32_f16 v[12:15], v[202:205], v[234:237], v[12:15]
	v_mfma_f32_16x16x32_f16 v[8:11], v[210:213], v[234:237], v[8:11]
	v_mfma_f32_16x16x32_f16 v[4:7], v[202:205], v[242:245], v[4:7]
	v_mfma_f32_16x16x32_f16 v[0:3], v[210:213], v[242:245], v[0:3]
	s_barrier
	s_add_i32 s30, s30, 2
	s_add_u32 s48, s48, 0x100
	s_addc_u32 s49, s49, 0
	s_add_u32 s75, s75, 0x100
	s_addc_u32 s76, s76, 0
	s_cmp_gt_u32 s30, 13
	s_cbranch_scc0 .LBB0_136
	s_and_b64 vcc, exec, s[10:11]
	s_cbranch_vccz .LBB0_139
	s_barrier

; #define PG8_STAGE(bufoff, gbase, voff) do { _Pragma("unroll") for (int _i = 0; _i < 2; ++_i) \
;         __builtin_amdgcn_global_load_lds((const unsigned*)((const char*)(gbase) + (voff)[_i]), (PG8_LAS unsigned*)(lds + (bufoff) + ldsw + _i * 8192), 16, 0, 0); } while (0)
; #define PG8_LDA(dst, b, h) do { _Pragma("unroll") for (int m = 0; m < 4; ++m) _Pragma("unroll") for (int k = 0; k < 2; ++k) dst[m][k] = *(const PG8_LAS bf16x8*)(lds + PG8_SA(b, h) + aoff + m * 2048 + k * 1024); } while (0)
; #define PG8_LDB(dst, b, h) do { _Pragma("unroll") for (int n = 0; n < 2; ++n) _Pragma("unroll") for (int k = 0; k < 2; ++k) dst[n][k] = *(const PG8_LAS bf16x8*)(lds + PG8_SB(b, h) + boff + n * 2048 + k * 1024); } while (0)
; #define PG8_WAIT_V(n) asm volatile("s_waitcnt vmcnt(" #n ")" ::: "memory")
; #define PG8_WAIT_L(n) asm volatile("s_waitcnt lgkmcnt(" #n ")" ::: "memory")
; #define PG8_BAR __builtin_amdgcn_s_barrier()
; #define PG8_SCHED __builtin_amdgcn_sched_barrier(0)
; template <class Epi, class Sched, bool ALIGN_EPI = false, bool SP2 = false, bool F16 = false>
; __device__ __forceinline__ void gemm_phase(PG8_LAS unsigned char* lds, const Gemm g, const Sched& S, const Epi& E) {
;     ...
;             if constexpr (SP2) {
;             PG8_LDB(B0, 0, 0); PG8_LDB(B1, 0, 1); PG8_SCHED; PG8_LDA(At, 0, 0); PG8_STAGE(PG8_SA(1, 1), a1 + hstep, voffA);
;             PG8_WAIT_V(8); PG8_WAIT_L(0); PG8_BAR; PG8_MMA(0, 0, At, B0); PG8_MMA(0, 1, At, B1); PG8_BAR; PG8_SCHED;
;             PG8_LDA(At, 0, 1); PG8_STAGE(PG8_SB(0, 0), b2, voffB); PG8_STAGE(PG8_SB(0, 1), b2 + hstep, voffB); PG8_STAGE(PG8_SA(0, 0), a2, voffA);
;             PG8_WAIT_V(8); PG8_WAIT_L(0); PG8_BAR; PG8_MMA(1, 0, At, B0); PG8_MMA(1, 1, At, B1); PG8_BAR; PG8_SCHED;
.LBB0_370:
	s_add_u32 s31, s54, 0xfffc0080
	s_addc_u32 s56, s55, -1
	s_add_i32 s79, 0, 0x10000
	s_cmp_eq_u32 s30, 12
	s_cselect_b32 s59, s19, s56
	s_cselect_b32 s58, s75, s31
	v_add_u32_e32 v138, s79, v141
	s_cselect_b32 s57, s17, s78
	s_cselect_b32 s56, s76, s77
	s_add_i32 s31, 0, 0x14000
	ds_read_b128 v[144:147], v138
	ds_read_b128 v[156:159], v138 offset:1024
	ds_read_b128 v[160:163], v138 offset:2048
	ds_read_b128 v[164:167], v138 offset:3072
	v_add_u32_e32 v138, s31, v141
	ds_read_b128 v[186:189], v138
	ds_read_b128 v[190:193], v138 offset:1024
	ds_read_b128 v[194:197], v138 offset:2048
	ds_read_b128 v[198:201], v138 offset:3072
	v_lshl_add_u64 v[138:139], s[54:55], 0, v[134:135]
	s_add_i32 m0, s49, 0xc000
	ds_read_b128 v[202:205], v143
	ds_read_b128 v[206:209], v143 offset:1024
	ds_read_b128 v[210:213], v143 offset:2048
	ds_read_b128 v[214:217], v143 offset:3072
	ds_read_b128 v[218:221], v143 offset:4096
	ds_read_b128 v[222:225], v143 offset:5120
	ds_read_b128 v[226:229], v143 offset:6144
	ds_read_b128 v[230:233], v143 offset:7168
	global_load_lds_dwordx4 v[138:139], off
	v_lshl_add_u64 v[138:139], s[54:55], 0, v[136:137]
	s_add_i32 m0, s49, 0xe000
	s_nop 0
	global_load_lds_dwordx4 v[138:139], off
	s_waitcnt vmcnt(8)
	s_waitcnt lgkmcnt(0)
	s_barrier
	s_waitcnt lgkmcnt(0)
	v_mfma_f32_16x16x32_bf16 v[124:127], v[144:147], v[202:205], v[124:127]
	v_mfma_f32_16x16x32_bf16 v[120:123], v[160:163], v[202:205], v[120:123]
	v_mfma_f32_16x16x32_bf16 v[116:119], v[144:147], v[210:213], v[116:119]
	v_mfma_f32_16x16x32_bf16 v[108:111], v[160:163], v[210:213], v[108:111]
	v_mfma_f32_16x16x32_bf16 v[100:103], v[144:147], v[218:221], v[100:103]
	v_mfma_f32_16x16x32_bf16 v[92:95], v[160:163], v[218:221], v[92:95]
	v_mfma_f32_16x16x32_bf16 v[84:87], v[144:147], v[226:229], v[84:87]
	v_mfma_f32_16x16x32_bf16 v[76:79], v[160:163], v[226:229], v[76:79]
	v_mfma_f32_16x16x32_bf16 v[124:127], v[156:159], v[206:209], v[124:127]
	v_mfma_f32_16x16x32_bf16 v[120:123], v[164:167], v[206:209], v[120:123]
	v_mfma_f32_16x16x32_bf16 v[116:119], v[156:159], v[214:217], v[116:119]
	v_mfma_f32_16x16x32_bf16 v[108:111], v[164:167], v[214:217], v[108:111]
	v_mfma_f32_16x16x32_bf16 v[100:103], v[156:159], v[222:225], v[100:103]
	v_mfma_f32_16x16x32_bf16 v[92:95], v[164:167], v[222:225], v[92:95]
	v_mfma_f32_16x16x32_bf16 v[84:87], v[156:159], v[230:233], v[84:87]
	v_mfma_f32_16x16x32_bf16 v[76:79], v[164:167], v[230:233], v[76:79]
	v_mfma_f32_16x16x32_bf16 v[112:115], v[186:189], v[202:205], v[112:115]
	v_mfma_f32_16x16x32_bf16 v[104:107], v[194:197], v[202:205], v[104:107]
	v_mfma_f32_16x16x32_bf16 v[96:99], v[186:189], v[210:213], v[96:99]
	v_mfma_f32_16x16x32_bf16 v[88:91], v[194:197], v[210:213], v[88:91]
	v_mfma_f32_16x16x32_bf16 v[80:83], v[186:189], v[218:221], v[80:83]
	v_mfma_f32_16x16x32_bf16 v[72:75], v[194:197], v[218:221], v[72:75]
	v_mfma_f32_16x16x32_bf16 v[68:71], v[186:189], v[226:229], v[68:71]
	v_mfma_f32_16x16x32_bf16 v[64:67], v[194:197], v[226:229], v[64:67]
	v_mfma_f32_16x16x32_bf16 v[112:115], v[190:193], v[206:209], v[112:115]
	v_mfma_f32_16x16x32_bf16 v[104:107], v[198:201], v[206:209], v[104:107]
	v_mfma_f32_16x16x32_bf16 v[96:99], v[190:193], v[214:217], v[96:99]
	v_mfma_f32_16x16x32_bf16 v[88:91], v[198:201], v[214:217], v[88:91]
	v_mfma_f32_16x16x32_bf16 v[80:83], v[190:193], v[222:225], v[80:83]
	v_mfma_f32_16x16x32_bf16 v[72:75], v[198:201], v[222:225], v[72:75]
	v_mfma_f32_16x16x32_bf16 v[68:71], v[190:193], v[230:233], v[68:71]
	v_mfma_f32_16x16x32_bf16 v[64:67], v[198:201], v[230:233], v[64:67]
	s_barrier
	s_add_i32 s79, s79, s63
	v_lshl_add_u64 v[138:139], s[56:57], 0, v[150:151]
	s_mov_b32 m0, s79
	ds_read_b128 v[202:205], v143 offset:16384
	ds_read_b128 v[206:209], v143 offset:17408
	ds_read_b128 v[210:213], v143 offset:18432
	ds_read_b128 v[214:217], v143 offset:19456
	ds_read_b128 v[218:221], v143 offset:20480
	ds_read_b128 v[222:225], v143 offset:21504
	ds_read_b128 v[226:229], v143 offset:22528
	ds_read_b128 v[230:233], v143 offset:23552
	global_load_lds_dwordx4 v[138:139], off
	s_add_i32 m0, s79, 0x2000
	s_add_u32 s80, s56, 0x40000
	v_lshl_add_u64 v[168:169], s[56:57], 0, v[128:129]
	s_addc_u32 s81, s57, 0
	s_add_i32 s31, s31, s63
	global_load_lds_dwordx4 v[168:169], off
	v_lshl_add_u64 v[234:235], s[80:81], 0, v[150:151]
	s_mov_b32 m0, s31
	v_lshl_add_u64 v[236:237], s[58:59], 0, v[130:131]
	global_load_lds_dwordx4 v[234:235], off
	v_lshl_add_u64 v[234:235], s[80:81], 0, v[128:129]
	s_add_i32 m0, s31, 0x2000
	s_nop 0
	global_load_lds_dwordx4 v[234:235], off
	v_lshl_add_u64 v[234:235], s[58:59], 0, v[132:133]
	s_mov_b32 m0, s49
	s_nop 0
	global_load_lds_dwordx4 v[234:235], off
	s_mov_b32 m0, s64
	s_nop 0
	global_load_lds_dwordx4 v[236:237], off
	s_waitcnt vmcnt(8)
	s_waitcnt lgkmcnt(0)
	s_barrier
; #define PG8_STAGE(bufoff, gbase, voff) do { _Pragma("unroll") for (int _i = 0; _i < 2; ++_i) \
;         __builtin_amdgcn_global_load_lds((const unsigned*)((const char*)(gbase) + (voff)[_i]), (PG8_LAS unsigned*)(lds + (bufoff) + ldsw + _i * 8192), 16, 0, 0); } while (0)
; #define PG8_LDA(dst, b, h) do { _Pragma("unroll") for (int m = 0; m < 4; ++m) _Pragma("unroll") for (int k = 0; k < 2; ++k) dst[m][k] = *(const PG8_LAS bf16x8*)(lds + PG8_SA(b, h) + aoff + m * 2048 + k * 1024); } while (0)
; #define PG8_LDB(dst, b, h) do { _Pragma("unroll") for (int n = 0; n < 2; ++n) _Pragma("unroll") for (int k = 0; k < 2; ++k) dst[n][k] = *(const PG8_LAS bf16x8*)(lds + PG8_SB(b, h) + boff + n * 2048 + k * 1024); } while (0)
; #define PG8_WAIT_V(n) asm volatile("s_waitcnt vmcnt(" #n ")" ::: "memory")
; #define PG8_WAIT_L(n) asm volatile("s_waitcnt lgkmcnt(" #n ")" ::: "memory")
; #define PG8_BAR __builtin_amdgcn_s_barrier()
; #define PG8_SCHED __builtin_amdgcn_sched_barrier(0)
; template <class Epi, class Sched, bool ALIGN_EPI = false, bool SP2 = false, bool F16 = false>
; __device__ __forceinline__ void gemm_phase(PG8_LAS unsigned char* lds, const Gemm g, const Sched& S, const Epi& E) {
;     ...
;             PG8_WAIT_V(8); PG8_WAIT_L(0); PG8_BAR; PG8_MMA(1, 0, At, B0); PG8_MMA(1, 1, At, B1); PG8_BAR; PG8_SCHED;
;             PG8_LDB(B0, 1, 0); PG8_LDB(B1, 1, 1); PG8_SCHED; PG8_LDA(At, 1, 0); PG8_STAGE(PG8_SA(0, 1), a2 + hstep, voffA);
;             PG8_WAIT_V(8); PG8_WAIT_L(0); PG8_BAR; PG8_MMA(0, 0, At, B0); PG8_MMA(0, 1, At, B1); PG8_BAR; PG8_SCHED;
;             PG8_LDA(At, 1, 1); PG8_STAGE(PG8_SB(1, 0), b3, voffB); PG8_STAGE(PG8_SB(1, 1), b3 + hstep, voffB); PG8_STAGE(PG8_SA(1, 0), a3, voffA);
	s_waitcnt lgkmcnt(0)
	v_mfma_f32_16x16x32_bf16 v[60:63], v[144:147], v[202:205], v[60:63]
	v_mfma_f32_16x16x32_bf16 v[56:59], v[160:163], v[202:205], v[56:59]
	v_mfma_f32_16x16x32_bf16 v[52:55], v[144:147], v[210:213], v[52:55]
	v_mfma_f32_16x16x32_bf16 v[44:47], v[160:163], v[210:213], v[44:47]
	v_mfma_f32_16x16x32_bf16 v[36:39], v[144:147], v[218:221], v[36:39]
	v_mfma_f32_16x16x32_bf16 v[28:31], v[160:163], v[218:221], v[28:31]
	v_mfma_f32_16x16x32_bf16 v[20:23], v[144:147], v[226:229], v[20:23]
	v_mfma_f32_16x16x32_bf16 v[12:15], v[160:163], v[226:229], v[12:15]
	v_mfma_f32_16x16x32_bf16 v[60:63], v[156:159], v[206:209], v[60:63]
	v_mfma_f32_16x16x32_bf16 v[56:59], v[164:167], v[206:209], v[56:59]
	v_mfma_f32_16x16x32_bf16 v[52:55], v[156:159], v[214:217], v[52:55]
	v_mfma_f32_16x16x32_bf16 v[44:47], v[164:167], v[214:217], v[44:47]
	v_mfma_f32_16x16x32_bf16 v[36:39], v[156:159], v[222:225], v[36:39]
	v_mfma_f32_16x16x32_bf16 v[28:31], v[164:167], v[222:225], v[28:31]
	v_mfma_f32_16x16x32_bf16 v[20:23], v[156:159], v[230:233], v[20:23]
	v_mfma_f32_16x16x32_bf16 v[12:15], v[164:167], v[230:233], v[12:15]
	v_mfma_f32_16x16x32_bf16 v[48:51], v[186:189], v[202:205], v[48:51]
	v_mfma_f32_16x16x32_bf16 v[40:43], v[194:197], v[202:205], v[40:43]
	v_mfma_f32_16x16x32_bf16 v[32:35], v[186:189], v[210:213], v[32:35]
	v_mfma_f32_16x16x32_bf16 v[24:27], v[194:197], v[210:213], v[24:27]
	v_mfma_f32_16x16x32_bf16 v[16:19], v[186:189], v[218:221], v[16:19]
	v_mfma_f32_16x16x32_bf16 v[8:11], v[194:197], v[218:221], v[8:11]
	v_mfma_f32_16x16x32_bf16 v[4:7], v[186:189], v[226:229], v[4:7]
	v_mfma_f32_16x16x32_bf16 v[0:3], v[194:197], v[226:229], v[0:3]
	v_mfma_f32_16x16x32_bf16 v[48:51], v[190:193], v[206:209], v[48:51]
	v_mfma_f32_16x16x32_bf16 v[40:43], v[198:201], v[206:209], v[40:43]
	v_mfma_f32_16x16x32_bf16 v[32:35], v[190:193], v[214:217], v[32:35]
	v_mfma_f32_16x16x32_bf16 v[24:27], v[198:201], v[214:217], v[24:27]
	v_mfma_f32_16x16x32_bf16 v[16:19], v[190:193], v[222:225], v[16:19]
	v_mfma_f32_16x16x32_bf16 v[8:11], v[198:201], v[222:225], v[8:11]
	v_mfma_f32_16x16x32_bf16 v[4:7], v[190:193], v[230:233], v[4:7]
	v_mfma_f32_16x16x32_bf16 v[0:3], v[198:201], v[230:233], v[0:3]
	s_barrier
	s_add_i32 s31, 0, 0x18000
	s_add_i32 s79, 0, 0x1c000
	v_add_u32_e32 v164, s31, v141
	v_add_u32_e32 v170, s79, v141
	ds_read_b128 v[144:147], v164
	ds_read_b128 v[156:159], v164 offset:1024
	ds_read_b128 v[160:163], v164 offset:2048
	ds_read_b128 v[164:167], v164 offset:3072
	ds_read_b128 v[186:189], v170
	ds_read_b128 v[190:193], v170 offset:1024
	ds_read_b128 v[194:197], v170 offset:2048
	ds_read_b128 v[198:201], v170 offset:3072
	s_add_u32 s58, s58, 0x40000
	s_addc_u32 s59, s59, 0
	s_mov_b32 m0, s65
	v_lshl_add_u64 v[238:239], s[58:59], 0, v[132:133]
	ds_read_b128 v[202:205], v143 offset:32768
	ds_read_b128 v[206:209], v143 offset:33792
	ds_read_b128 v[210:213], v143 offset:34816
	ds_read_b128 v[214:217], v143 offset:35840
	ds_read_b128 v[218:221], v143 offset:36864
	ds_read_b128 v[222:225], v143 offset:37888
	ds_read_b128 v[226:229], v143 offset:38912
	ds_read_b128 v[230:233], v143 offset:39936
	global_load_lds_dwordx4 v[238:239], off
	v_lshl_add_u64 v[238:239], s[58:59], 0, v[130:131]
	s_mov_b32 m0, s66
	s_nop 0
	global_load_lds_dwordx4 v[238:239], off
	s_waitcnt vmcnt(8)
	s_waitcnt lgkmcnt(0)
	s_barrier
	s_waitcnt lgkmcnt(0)
	v_mfma_f32_16x16x32_bf16 v[124:127], v[144:147], v[202:205], v[124:127]
	v_mfma_f32_16x16x32_bf16 v[120:123], v[160:163], v[202:205], v[120:123]
	v_mfma_f32_16x16x32_bf16 v[116:119], v[144:147], v[210:213], v[116:119]
	v_mfma_f32_16x16x32_bf16 v[108:111], v[160:163], v[210:213], v[108:111]
	v_mfma_f32_16x16x32_bf16 v[100:103], v[144:147], v[218:221], v[100:103]
	v_mfma_f32_16x16x32_bf16 v[92:95], v[160:163], v[218:221], v[92:95]
	v_mfma_f32_16x16x32_bf16 v[84:87], v[144:147], v[226:229], v[84:87]
	v_mfma_f32_16x16x32_bf16 v[76:79], v[160:163], v[226:229], v[76:79]
	v_mfma_f32_16x16x32_bf16 v[124:127], v[156:159], v[206:209], v[124:127]
	v_mfma_f32_16x16x32_bf16 v[120:123], v[164:167], v[206:209], v[120:123]
	v_mfma_f32_16x16x32_bf16 v[116:119], v[156:159], v[214:217], v[116:119]
	v_mfma_f32_16x16x32_bf16 v[108:111], v[164:167], v[214:217], v[108:111]
	v_mfma_f32_16x16x32_bf16 v[100:103], v[156:159], v[222:225], v[100:103]
	v_mfma_f32_16x16x32_bf16 v[92:95], v[164:167], v[222:225], v[92:95]
	v_mfma_f32_16x16x32_bf16 v[84:87], v[156:159], v[230:233], v[84:87]
	v_mfma_f32_16x16x32_bf16 v[76:79], v[164:167], v[230:233], v[76:79]
	v_mfma_f32_16x16x32_bf16 v[112:115], v[186:189], v[202:205], v[112:115]
	v_mfma_f32_16x16x32_bf16 v[104:107], v[194:197], v[202:205], v[104:107]
	v_mfma_f32_16x16x32_bf16 v[96:99], v[186:189], v[210:213], v[96:99]
	v_mfma_f32_16x16x32_bf16 v[88:91], v[194:197], v[210:213], v[88:91]
	v_mfma_f32_16x16x32_bf16 v[80:83], v[186:189], v[218:221], v[80:83]
	v_mfma_f32_16x16x32_bf16 v[72:75], v[194:197], v[218:221], v[72:75]
	v_mfma_f32_16x16x32_bf16 v[68:71], v[186:189], v[226:229], v[68:71]
	v_mfma_f32_16x16x32_bf16 v[64:67], v[194:197], v[226:229], v[64:67]
	v_mfma_f32_16x16x32_bf16 v[112:115], v[190:193], v[206:209], v[112:115]
	v_mfma_f32_16x16x32_bf16 v[104:107], v[198:201], v[206:209], v[104:107]
	v_mfma_f32_16x16x32_bf16 v[96:99], v[190:193], v[214:217], v[96:99]
	v_mfma_f32_16x16x32_bf16 v[88:91], v[198:201], v[214:217], v[88:91]
	v_mfma_f32_16x16x32_bf16 v[80:83], v[190:193], v[222:225], v[80:83]
	v_mfma_f32_16x16x32_bf16 v[72:75], v[198:201], v[222:225], v[72:75]
	v_mfma_f32_16x16x32_bf16 v[68:71], v[190:193], v[230:233], v[68:71]
	v_mfma_f32_16x16x32_bf16 v[64:67], v[198:201], v[230:233], v[64:67]
	s_barrier
; #define PG8_STAGE(bufoff, gbase, voff) do { _Pragma("unroll") for (int _i = 0; _i < 2; ++_i) \
;         __builtin_amdgcn_global_load_lds((const unsigned*)((const char*)(gbase) + (voff)[_i]), (PG8_LAS unsigned*)(lds + (bufoff) + ldsw + _i * 8192), 16, 0, 0); } while (0)
; #define PG8_LDA(dst, b, h) do { _Pragma("unroll") for (int m = 0; m < 4; ++m) _Pragma("unroll") for (int k = 0; k < 2; ++k) dst[m][k] = *(const PG8_LAS bf16x8*)(lds + PG8_SA(b, h) + aoff + m * 2048 + k * 1024); } while (0)
; #define PG8_WAIT_V(n) asm volatile("s_waitcnt vmcnt(" #n ")" ::: "memory")
; #define PG8_WAIT_L(n) asm volatile("s_waitcnt lgkmcnt(" #n ")" ::: "memory")
; #define PG8_BAR __builtin_amdgcn_s_barrier()
; #define PG8_SCHED __builtin_amdgcn_sched_barrier(0)
; template <class Epi, class Sched, bool ALIGN_EPI = false, bool SP2 = false, bool F16 = false>
; __device__ __forceinline__ void gemm_phase(PG8_LAS unsigned char* lds, const Gemm g, const Sched& S, const Epi& E) {
;     ...
;         for (int t = 0; t < nt; t += 2) {
;     ...
;             PG8_LDA(At, 1, 1); PG8_STAGE(PG8_SB(1, 0), b3, voffB); PG8_STAGE(PG8_SB(1, 1), b3 + hstep, voffB); PG8_STAGE(PG8_SA(1, 0), a3, voffA);
;             PG8_WAIT_V(8); PG8_WAIT_L(0); PG8_BAR; PG8_MMA(1, 0, At, B0); PG8_MMA(1, 1, At, B1); PG8_BAR; PG8_SCHED;
	s_add_i32 s31, s31, s63
	v_lshl_add_u64 v[138:139], v[138:139], 0, s[22:23]
	s_mov_b32 m0, s31
	ds_read_b128 v[202:205], v143 offset:49152
	ds_read_b128 v[206:209], v143 offset:50176
	ds_read_b128 v[210:213], v143 offset:51200
	ds_read_b128 v[214:217], v143 offset:52224
	ds_read_b128 v[218:221], v143 offset:53248
	ds_read_b128 v[222:225], v143 offset:54272
	ds_read_b128 v[226:229], v143 offset:55296
	ds_read_b128 v[230:233], v143 offset:56320
	global_load_lds_dwordx4 v[138:139], off
	s_add_i32 m0, s31, 0x2000
	s_add_u32 s56, s56, 0x40080
	v_lshl_add_u64 v[138:139], v[168:169], 0, s[22:23]
	s_addc_u32 s57, s57, 0
	s_add_i32 s31, s79, s63
	global_load_lds_dwordx4 v[138:139], off
	v_lshl_add_u64 v[138:139], s[56:57], 0, v[150:151]
	s_mov_b32 m0, s31
	s_nop 0
	global_load_lds_dwordx4 v[138:139], off
	v_lshl_add_u64 v[138:139], s[56:57], 0, v[128:129]
	s_add_i32 m0, s31, 0x2000
	s_nop 0
	global_load_lds_dwordx4 v[138:139], off
	v_lshl_add_u64 v[138:139], v[234:235], 0, s[22:23]
	s_mov_b32 m0, s68
	s_nop 0
	global_load_lds_dwordx4 v[138:139], off
	v_lshl_add_u64 v[138:139], v[236:237], 0, s[22:23]
	s_mov_b32 m0, s69
	s_nop 0
	global_load_lds_dwordx4 v[138:139], off
	s_waitcnt vmcnt(8)
	s_waitcnt lgkmcnt(0)
	s_barrier
	s_waitcnt lgkmcnt(0)
	v_mfma_f32_16x16x32_bf16 v[60:63], v[144:147], v[202:205], v[60:63]
	v_mfma_f32_16x16x32_bf16 v[56:59], v[160:163], v[202:205], v[56:59]
	v_mfma_f32_16x16x32_bf16 v[52:55], v[144:147], v[210:213], v[52:55]
	v_mfma_f32_16x16x32_bf16 v[44:47], v[160:163], v[210:213], v[44:47]
	v_mfma_f32_16x16x32_bf16 v[36:39], v[144:147], v[218:221], v[36:39]
	v_mfma_f32_16x16x32_bf16 v[28:31], v[160:163], v[218:221], v[28:31]
	v_mfma_f32_16x16x32_bf16 v[20:23], v[144:147], v[226:229], v[20:23]
	v_mfma_f32_16x16x32_bf16 v[12:15], v[160:163], v[226:229], v[12:15]
	v_mfma_f32_16x16x32_bf16 v[60:63], v[156:159], v[206:209], v[60:63]
	v_mfma_f32_16x16x32_bf16 v[56:59], v[164:167], v[206:209], v[56:59]
	v_mfma_f32_16x16x32_bf16 v[52:55], v[156:159], v[214:217], v[52:55]
	v_mfma_f32_16x16x32_bf16 v[44:47], v[164:167], v[214:217], v[44:47]
	v_mfma_f32_16x16x32_bf16 v[36:39], v[156:159], v[222:225], v[36:39]
	v_mfma_f32_16x16x32_bf16 v[28:31], v[164:167], v[222:225], v[28:31]
	v_mfma_f32_16x16x32_bf16 v[20:23], v[156:159], v[230:233], v[20:23]
	v_mfma_f32_16x16x32_bf16 v[12:15], v[164:167], v[230:233], v[12:15]
	v_mfma_f32_16x16x32_bf16 v[48:51], v[186:189], v[202:205], v[48:51]
	v_mfma_f32_16x16x32_bf16 v[40:43], v[194:197], v[202:205], v[40:43]
	v_mfma_f32_16x16x32_bf16 v[32:35], v[186:189], v[210:213], v[32:35]
	v_mfma_f32_16x16x32_bf16 v[24:27], v[194:197], v[210:213], v[24:27]
	v_mfma_f32_16x16x32_bf16 v[16:19], v[186:189], v[218:221], v[16:19]
	v_mfma_f32_16x16x32_bf16 v[8:11], v[194:197], v[218:221], v[8:11]
	v_mfma_f32_16x16x32_bf16 v[4:7], v[186:189], v[226:229], v[4:7]
	v_mfma_f32_16x16x32_bf16 v[0:3], v[194:197], v[226:229], v[0:3]
	v_mfma_f32_16x16x32_bf16 v[48:51], v[190:193], v[206:209], v[48:51]
	v_mfma_f32_16x16x32_bf16 v[40:43], v[198:201], v[206:209], v[40:43]
	v_mfma_f32_16x16x32_bf16 v[32:35], v[190:193], v[214:217], v[32:35]
	v_mfma_f32_16x16x32_bf16 v[24:27], v[198:201], v[214:217], v[24:27]
	v_mfma_f32_16x16x32_bf16 v[16:19], v[190:193], v[222:225], v[16:19]
	v_mfma_f32_16x16x32_bf16 v[8:11], v[198:201], v[222:225], v[8:11]
	v_mfma_f32_16x16x32_bf16 v[4:7], v[190:193], v[230:233], v[4:7]
	v_mfma_f32_16x16x32_bf16 v[0:3], v[198:201], v[230:233], v[0:3]
	s_barrier
	s_add_i32 s30, s30, 2
	s_add_u32 s54, s54, 0x100
	s_addc_u32 s55, s55, 0
	s_add_u32 s77, s77, 0x100
	s_addc_u32 s78, s78, 0
	s_cmp_gt_u32 s30, 13
	s_cbranch_scc0 .LBB0_370
	s_and_b64 vcc, exec, s[12:13]
	s_cbranch_vccz .LBB0_373
	s_barrier

; #define PG8_STAGE(bufoff, gbase, voff) do { _Pragma("unroll") for (int _i = 0; _i < 2; ++_i) \
;         __builtin_amdgcn_global_load_lds((const unsigned*)((const char*)(gbase) + (voff)[_i]), (PG8_LAS unsigned*)(lds + (bufoff) + ldsw + _i * 8192), 16, 0, 0); } while (0)
; #define PG8_LDA(dst, b, h) do { _Pragma("unroll") for (int m = 0; m < 4; ++m) _Pragma("unroll") for (int k = 0; k < 2; ++k) dst[m][k] = *(const PG8_LAS bf16x8*)(lds + PG8_SA(b, h) + aoff + m * 2048 + k * 1024); } while (0)
; #define PG8_LDB(dst, b, h) do { _Pragma("unroll") for (int n = 0; n < 2; ++n) _Pragma("unroll") for (int k = 0; k < 2; ++k) dst[n][k] = *(const PG8_LAS bf16x8*)(lds + PG8_SB(b, h) + boff + n * 2048 + k * 1024); } while (0)
; #define PG8_WAIT_V(n) asm volatile("s_waitcnt vmcnt(" #n ")" ::: "memory")
; #define PG8_WAIT_L(n) asm volatile("s_waitcnt lgkmcnt(" #n ")" ::: "memory")
; #define PG8_BAR __builtin_amdgcn_s_barrier()
; #define PG8_SCHED __builtin_amdgcn_sched_barrier(0)
; template <class Epi, class Sched, bool ALIGN_EPI = false, bool SP2 = false, bool F16 = false>
; __device__ __forceinline__ void gemm_phase(PG8_LAS unsigned char* lds, const Gemm g, const Sched& S, const Epi& E) {
;     ...
;             if constexpr (SP2) {
;             PG8_LDB(B0, 0, 0); PG8_LDB(B1, 0, 1); PG8_SCHED; PG8_LDA(At, 0, 0); PG8_STAGE(PG8_SA(1, 1), a1 + hstep, voffA);
;             PG8_WAIT_V(8); PG8_WAIT_L(0); PG8_BAR; PG8_MMA(0, 0, At, B0); PG8_MMA(0, 1, At, B1); PG8_BAR; PG8_SCHED;
;             PG8_LDA(At, 0, 1); PG8_STAGE(PG8_SB(0, 0), b2, voffB); PG8_STAGE(PG8_SB(0, 1), b2 + hstep, voffB); PG8_STAGE(PG8_SA(0, 0), a2, voffA);
;             PG8_WAIT_V(8); PG8_WAIT_L(0); PG8_BAR; PG8_MMA(1, 0, At, B0); PG8_MMA(1, 1, At, B1); PG8_BAR; PG8_SCHED;
.LBB0_515:
	s_add_u32 s31, s56, 0xfffc0080
	s_addc_u32 s58, s57, -1
	s_add_i32 s85, 0, 0x10000
	s_cmp_eq_u32 s30, 12
	s_cselect_b32 s61, s49, s58
	s_cselect_b32 s60, s81, s31
	v_add_u32_e32 v138, s85, v141
	s_cselect_b32 s59, s19, s84
	s_cselect_b32 s58, s82, s83
	s_add_i32 s31, 0, 0x14000
	ds_read_b128 v[144:147], v138
	ds_read_b128 v[156:159], v138 offset:1024
	ds_read_b128 v[160:163], v138 offset:2048
	ds_read_b128 v[164:167], v138 offset:3072
	v_add_u32_e32 v138, s31, v141
	ds_read_b128 v[186:189], v138
	ds_read_b128 v[190:193], v138 offset:1024
	ds_read_b128 v[194:197], v138 offset:2048
	ds_read_b128 v[198:201], v138 offset:3072
	v_lshl_add_u64 v[138:139], s[56:57], 0, v[134:135]
	s_add_i32 m0, s74, 0xc000
	ds_read_b128 v[202:205], v143
	ds_read_b128 v[206:209], v143 offset:1024
	ds_read_b128 v[210:213], v143 offset:2048
	ds_read_b128 v[214:217], v143 offset:3072
	ds_read_b128 v[218:221], v143 offset:4096
	ds_read_b128 v[222:225], v143 offset:5120
	ds_read_b128 v[226:229], v143 offset:6144
	ds_read_b128 v[230:233], v143 offset:7168
	global_load_lds_dwordx4 v[138:139], off
	v_lshl_add_u64 v[138:139], s[56:57], 0, v[136:137]
	s_add_i32 m0, s74, 0xe000
	s_nop 0
	global_load_lds_dwordx4 v[138:139], off
	s_waitcnt vmcnt(8)
	s_waitcnt lgkmcnt(0)
	s_barrier
	s_waitcnt lgkmcnt(0)
	v_mfma_f32_16x16x32_f16 v[124:127], v[144:147], v[202:205], v[124:127]
	v_mfma_f32_16x16x32_f16 v[116:119], v[160:163], v[202:205], v[116:119]
	v_mfma_f32_16x16x32_f16 v[108:111], v[144:147], v[210:213], v[108:111]
	v_mfma_f32_16x16x32_f16 v[100:103], v[160:163], v[210:213], v[100:103]
	v_mfma_f32_16x16x32_f16 v[92:95], v[144:147], v[218:221], v[92:95]
	v_mfma_f32_16x16x32_f16 v[84:87], v[160:163], v[218:221], v[84:87]
	v_mfma_f32_16x16x32_f16 v[76:79], v[144:147], v[226:229], v[76:79]
	v_mfma_f32_16x16x32_f16 v[68:71], v[160:163], v[226:229], v[68:71]
	v_mfma_f32_16x16x32_f16 v[124:127], v[156:159], v[206:209], v[124:127]
	v_mfma_f32_16x16x32_f16 v[116:119], v[164:167], v[206:209], v[116:119]
	v_mfma_f32_16x16x32_f16 v[108:111], v[156:159], v[214:217], v[108:111]
	v_mfma_f32_16x16x32_f16 v[100:103], v[164:167], v[214:217], v[100:103]
	v_mfma_f32_16x16x32_f16 v[92:95], v[156:159], v[222:225], v[92:95]
	v_mfma_f32_16x16x32_f16 v[84:87], v[164:167], v[222:225], v[84:87]
	v_mfma_f32_16x16x32_f16 v[76:79], v[156:159], v[230:233], v[76:79]
	v_mfma_f32_16x16x32_f16 v[68:71], v[164:167], v[230:233], v[68:71]
	v_mfma_f32_16x16x32_f16 v[120:123], v[186:189], v[202:205], v[120:123]
	v_mfma_f32_16x16x32_f16 v[112:115], v[194:197], v[202:205], v[112:115]
	v_mfma_f32_16x16x32_f16 v[104:107], v[186:189], v[210:213], v[104:107]
	v_mfma_f32_16x16x32_f16 v[96:99], v[194:197], v[210:213], v[96:99]
	v_mfma_f32_16x16x32_f16 v[88:91], v[186:189], v[218:221], v[88:91]
	v_mfma_f32_16x16x32_f16 v[80:83], v[194:197], v[218:221], v[80:83]
	v_mfma_f32_16x16x32_f16 v[72:75], v[186:189], v[226:229], v[72:75]
	v_mfma_f32_16x16x32_f16 v[64:67], v[194:197], v[226:229], v[64:67]
	v_mfma_f32_16x16x32_f16 v[120:123], v[190:193], v[206:209], v[120:123]
	v_mfma_f32_16x16x32_f16 v[112:115], v[198:201], v[206:209], v[112:115]
	v_mfma_f32_16x16x32_f16 v[104:107], v[190:193], v[214:217], v[104:107]
	v_mfma_f32_16x16x32_f16 v[96:99], v[198:201], v[214:217], v[96:99]
	v_mfma_f32_16x16x32_f16 v[88:91], v[190:193], v[222:225], v[88:91]
	v_mfma_f32_16x16x32_f16 v[80:83], v[198:201], v[222:225], v[80:83]
	v_mfma_f32_16x16x32_f16 v[72:75], v[190:193], v[230:233], v[72:75]
	v_mfma_f32_16x16x32_f16 v[64:67], v[198:201], v[230:233], v[64:67]
	s_barrier
	s_add_i32 s85, s85, s69
	v_lshl_add_u64 v[138:139], s[58:59], 0, v[150:151]
	s_mov_b32 m0, s85
	ds_read_b128 v[202:205], v143 offset:16384
	ds_read_b128 v[206:209], v143 offset:17408
	ds_read_b128 v[210:213], v143 offset:18432
	ds_read_b128 v[214:217], v143 offset:19456
	ds_read_b128 v[218:221], v143 offset:20480
	ds_read_b128 v[222:225], v143 offset:21504
	ds_read_b128 v[226:229], v143 offset:22528
	ds_read_b128 v[230:233], v143 offset:23552
	global_load_lds_dwordx4 v[138:139], off
	s_add_i32 m0, s85, 0x2000
	s_add_u32 s90, s58, 0x40000
	v_lshl_add_u64 v[168:169], s[58:59], 0, v[128:129]
	s_addc_u32 s91, s59, 0
	s_add_i32 s31, s31, s69
	global_load_lds_dwordx4 v[168:169], off
	v_lshl_add_u64 v[234:235], s[90:91], 0, v[150:151]
	s_mov_b32 m0, s31
	v_lshl_add_u64 v[236:237], s[60:61], 0, v[130:131]
	global_load_lds_dwordx4 v[234:235], off
	v_lshl_add_u64 v[234:235], s[90:91], 0, v[128:129]
	s_add_i32 m0, s31, 0x2000
	s_nop 0
	global_load_lds_dwordx4 v[234:235], off
	v_lshl_add_u64 v[234:235], s[60:61], 0, v[132:133]
	s_mov_b32 m0, s74
	s_nop 0
	global_load_lds_dwordx4 v[234:235], off
	s_mov_b32 m0, s75
	s_nop 0
	global_load_lds_dwordx4 v[236:237], off
	s_waitcnt vmcnt(8)
	s_waitcnt lgkmcnt(0)
	s_barrier
; #define PG8_STAGE(bufoff, gbase, voff) do { _Pragma("unroll") for (int _i = 0; _i < 2; ++_i) \
;         __builtin_amdgcn_global_load_lds((const unsigned*)((const char*)(gbase) + (voff)[_i]), (PG8_LAS unsigned*)(lds + (bufoff) + ldsw + _i * 8192), 16, 0, 0); } while (0)
; #define PG8_LDA(dst, b, h) do { _Pragma("unroll") for (int m = 0; m < 4; ++m) _Pragma("unroll") for (int k = 0; k < 2; ++k) dst[m][k] = *(const PG8_LAS bf16x8*)(lds + PG8_SA(b, h) + aoff + m * 2048 + k * 1024); } while (0)
; #define PG8_LDB(dst, b, h) do { _Pragma("unroll") for (int n = 0; n < 2; ++n) _Pragma("unroll") for (int k = 0; k < 2; ++k) dst[n][k] = *(const PG8_LAS bf16x8*)(lds + PG8_SB(b, h) + boff + n * 2048 + k * 1024); } while (0)
; #define PG8_WAIT_V(n) asm volatile("s_waitcnt vmcnt(" #n ")" ::: "memory")
; #define PG8_WAIT_L(n) asm volatile("s_waitcnt lgkmcnt(" #n ")" ::: "memory")
; #define PG8_BAR __builtin_amdgcn_s_barrier()
; #define PG8_SCHED __builtin_amdgcn_sched_barrier(0)
; template <class Epi, class Sched, bool ALIGN_EPI = false, bool SP2 = false, bool F16 = false>
; __device__ __forceinline__ void gemm_phase(PG8_LAS unsigned char* lds, const Gemm g, const Sched& S, const Epi& E) {
;     ...
;             PG8_WAIT_V(8); PG8_WAIT_L(0); PG8_BAR; PG8_MMA(1, 0, At, B0); PG8_MMA(1, 1, At, B1); PG8_BAR; PG8_SCHED;
;             PG8_LDB(B0, 1, 0); PG8_LDB(B1, 1, 1); PG8_SCHED; PG8_LDA(At, 1, 0); PG8_STAGE(PG8_SA(0, 1), a2 + hstep, voffA);
;             PG8_WAIT_V(8); PG8_WAIT_L(0); PG8_BAR; PG8_MMA(0, 0, At, B0); PG8_MMA(0, 1, At, B1); PG8_BAR; PG8_SCHED;
;             PG8_LDA(At, 1, 1); PG8_STAGE(PG8_SB(1, 0), b3, voffB); PG8_STAGE(PG8_SB(1, 1), b3 + hstep, voffB); PG8_STAGE(PG8_SA(1, 0), a3, voffA);
	s_waitcnt lgkmcnt(0)
	v_mfma_f32_16x16x32_f16 v[60:63], v[144:147], v[202:205], v[60:63]
	v_mfma_f32_16x16x32_f16 v[52:55], v[160:163], v[202:205], v[52:55]
	v_mfma_f32_16x16x32_f16 v[44:47], v[144:147], v[210:213], v[44:47]
	v_mfma_f32_16x16x32_f16 v[36:39], v[160:163], v[210:213], v[36:39]
	v_mfma_f32_16x16x32_f16 v[28:31], v[144:147], v[218:221], v[28:31]
	v_mfma_f32_16x16x32_f16 v[20:23], v[160:163], v[218:221], v[20:23]
	v_mfma_f32_16x16x32_f16 v[12:15], v[144:147], v[226:229], v[12:15]
	v_mfma_f32_16x16x32_f16 v[4:7], v[160:163], v[226:229], v[4:7]
	v_mfma_f32_16x16x32_f16 v[60:63], v[156:159], v[206:209], v[60:63]
	v_mfma_f32_16x16x32_f16 v[52:55], v[164:167], v[206:209], v[52:55]
	v_mfma_f32_16x16x32_f16 v[44:47], v[156:159], v[214:217], v[44:47]
	v_mfma_f32_16x16x32_f16 v[36:39], v[164:167], v[214:217], v[36:39]
	v_mfma_f32_16x16x32_f16 v[28:31], v[156:159], v[222:225], v[28:31]
	v_mfma_f32_16x16x32_f16 v[20:23], v[164:167], v[222:225], v[20:23]
	v_mfma_f32_16x16x32_f16 v[12:15], v[156:159], v[230:233], v[12:15]
	v_mfma_f32_16x16x32_f16 v[4:7], v[164:167], v[230:233], v[4:7]
	v_mfma_f32_16x16x32_f16 v[56:59], v[186:189], v[202:205], v[56:59]
	v_mfma_f32_16x16x32_f16 v[48:51], v[194:197], v[202:205], v[48:51]
	v_mfma_f32_16x16x32_f16 v[40:43], v[186:189], v[210:213], v[40:43]
	v_mfma_f32_16x16x32_f16 v[32:35], v[194:197], v[210:213], v[32:35]
	v_mfma_f32_16x16x32_f16 v[24:27], v[186:189], v[218:221], v[24:27]
	v_mfma_f32_16x16x32_f16 v[16:19], v[194:197], v[218:221], v[16:19]
	v_mfma_f32_16x16x32_f16 v[8:11], v[186:189], v[226:229], v[8:11]
	v_mfma_f32_16x16x32_f16 v[0:3], v[194:197], v[226:229], v[0:3]
	v_mfma_f32_16x16x32_f16 v[56:59], v[190:193], v[206:209], v[56:59]
	v_mfma_f32_16x16x32_f16 v[48:51], v[198:201], v[206:209], v[48:51]
	v_mfma_f32_16x16x32_f16 v[40:43], v[190:193], v[214:217], v[40:43]
	v_mfma_f32_16x16x32_f16 v[32:35], v[198:201], v[214:217], v[32:35]
	v_mfma_f32_16x16x32_f16 v[24:27], v[190:193], v[222:225], v[24:27]
	v_mfma_f32_16x16x32_f16 v[16:19], v[198:201], v[222:225], v[16:19]
	v_mfma_f32_16x16x32_f16 v[8:11], v[190:193], v[230:233], v[8:11]
	v_mfma_f32_16x16x32_f16 v[0:3], v[198:201], v[230:233], v[0:3]
	s_barrier
	s_add_i32 s31, 0, 0x18000
	s_add_i32 s85, 0, 0x1c000
	v_add_u32_e32 v164, s31, v141
	v_add_u32_e32 v170, s85, v141
	ds_read_b128 v[144:147], v164
	ds_read_b128 v[156:159], v164 offset:1024
	ds_read_b128 v[160:163], v164 offset:2048
	ds_read_b128 v[164:167], v164 offset:3072
	ds_read_b128 v[186:189], v170
	ds_read_b128 v[190:193], v170 offset:1024
	ds_read_b128 v[194:197], v170 offset:2048
	ds_read_b128 v[198:201], v170 offset:3072
	s_add_u32 s60, s60, 0x40000
	s_addc_u32 s61, s61, 0
	s_mov_b32 m0, s76
	v_lshl_add_u64 v[238:239], s[60:61], 0, v[132:133]
	ds_read_b128 v[202:205], v143 offset:32768
	ds_read_b128 v[206:209], v143 offset:33792
	ds_read_b128 v[210:213], v143 offset:34816
	ds_read_b128 v[214:217], v143 offset:35840
	ds_read_b128 v[218:221], v143 offset:36864
	ds_read_b128 v[222:225], v143 offset:37888
	ds_read_b128 v[226:229], v143 offset:38912
	ds_read_b128 v[230:233], v143 offset:39936
	global_load_lds_dwordx4 v[238:239], off
	v_lshl_add_u64 v[238:239], s[60:61], 0, v[130:131]
	s_mov_b32 m0, s77
	s_nop 0
	global_load_lds_dwordx4 v[238:239], off
	s_waitcnt vmcnt(8)
	s_waitcnt lgkmcnt(0)
	s_barrier
	s_waitcnt lgkmcnt(0)
	v_mfma_f32_16x16x32_f16 v[124:127], v[144:147], v[202:205], v[124:127]
	v_mfma_f32_16x16x32_f16 v[116:119], v[160:163], v[202:205], v[116:119]
	v_mfma_f32_16x16x32_f16 v[108:111], v[144:147], v[210:213], v[108:111]
	v_mfma_f32_16x16x32_f16 v[100:103], v[160:163], v[210:213], v[100:103]
	v_mfma_f32_16x16x32_f16 v[92:95], v[144:147], v[218:221], v[92:95]
	v_mfma_f32_16x16x32_f16 v[84:87], v[160:163], v[218:221], v[84:87]
	v_mfma_f32_16x16x32_f16 v[76:79], v[144:147], v[226:229], v[76:79]
	v_mfma_f32_16x16x32_f16 v[68:71], v[160:163], v[226:229], v[68:71]
	v_mfma_f32_16x16x32_f16 v[124:127], v[156:159], v[206:209], v[124:127]
	v_mfma_f32_16x16x32_f16 v[116:119], v[164:167], v[206:209], v[116:119]
	v_mfma_f32_16x16x32_f16 v[108:111], v[156:159], v[214:217], v[108:111]
	v_mfma_f32_16x16x32_f16 v[100:103], v[164:167], v[214:217], v[100:103]
	v_mfma_f32_16x16x32_f16 v[92:95], v[156:159], v[222:225], v[92:95]
	v_mfma_f32_16x16x32_f16 v[84:87], v[164:167], v[222:225], v[84:87]
	v_mfma_f32_16x16x32_f16 v[76:79], v[156:159], v[230:233], v[76:79]
	v_mfma_f32_16x16x32_f16 v[68:71], v[164:167], v[230:233], v[68:71]
	v_mfma_f32_16x16x32_f16 v[120:123], v[186:189], v[202:205], v[120:123]
	v_mfma_f32_16x16x32_f16 v[112:115], v[194:197], v[202:205], v[112:115]
	v_mfma_f32_16x16x32_f16 v[104:107], v[186:189], v[210:213], v[104:107]
	v_mfma_f32_16x16x32_f16 v[96:99], v[194:197], v[210:213], v[96:99]
	v_mfma_f32_16x16x32_f16 v[88:91], v[186:189], v[218:221], v[88:91]
	v_mfma_f32_16x16x32_f16 v[80:83], v[194:197], v[218:221], v[80:83]
	v_mfma_f32_16x16x32_f16 v[72:75], v[186:189], v[226:229], v[72:75]
	v_mfma_f32_16x16x32_f16 v[64:67], v[194:197], v[226:229], v[64:67]
	v_mfma_f32_16x16x32_f16 v[120:123], v[190:193], v[206:209], v[120:123]
	v_mfma_f32_16x16x32_f16 v[112:115], v[198:201], v[206:209], v[112:115]
	v_mfma_f32_16x16x32_f16 v[104:107], v[190:193], v[214:217], v[104:107]
	v_mfma_f32_16x16x32_f16 v[96:99], v[198:201], v[214:217], v[96:99]
	v_mfma_f32_16x16x32_f16 v[88:91], v[190:193], v[222:225], v[88:91]
	v_mfma_f32_16x16x32_f16 v[80:83], v[198:201], v[222:225], v[80:83]
	v_mfma_f32_16x16x32_f16 v[72:75], v[190:193], v[230:233], v[72:75]
	v_mfma_f32_16x16x32_f16 v[64:67], v[198:201], v[230:233], v[64:67]
	s_barrier
; #define PG8_STAGE(bufoff, gbase, voff) do { _Pragma("unroll") for (int _i = 0; _i < 2; ++_i) \
;         __builtin_amdgcn_global_load_lds((const unsigned*)((const char*)(gbase) + (voff)[_i]), (PG8_LAS unsigned*)(lds + (bufoff) + ldsw + _i * 8192), 16, 0, 0); } while (0)
; #define PG8_LDA(dst, b, h) do { _Pragma("unroll") for (int m = 0; m < 4; ++m) _Pragma("unroll") for (int k = 0; k < 2; ++k) dst[m][k] = *(const PG8_LAS bf16x8*)(lds + PG8_SA(b, h) + aoff + m * 2048 + k * 1024); } while (0)
; #define PG8_WAIT_V(n) asm volatile("s_waitcnt vmcnt(" #n ")" ::: "memory")
; #define PG8_WAIT_L(n) asm volatile("s_waitcnt lgkmcnt(" #n ")" ::: "memory")
; #define PG8_BAR __builtin_amdgcn_s_barrier()
; #define PG8_SCHED __builtin_amdgcn_sched_barrier(0)
; template <class Epi, class Sched, bool ALIGN_EPI = false, bool SP2 = false, bool F16 = false>
; __device__ __forceinline__ void gemm_phase(PG8_LAS unsigned char* lds, const Gemm g, const Sched& S, const Epi& E) {
;     ...
;         for (int t = 0; t < nt; t += 2) {
;     ...
;             PG8_LDA(At, 1, 1); PG8_STAGE(PG8_SB(1, 0), b3, voffB); PG8_STAGE(PG8_SB(1, 1), b3 + hstep, voffB); PG8_STAGE(PG8_SA(1, 0), a3, voffA);
;             PG8_WAIT_V(8); PG8_WAIT_L(0); PG8_BAR; PG8_MMA(1, 0, At, B0); PG8_MMA(1, 1, At, B1); PG8_BAR; PG8_SCHED;
	s_add_i32 s31, s31, s69
	v_lshl_add_u64 v[138:139], v[138:139], 0, s[22:23]
	s_mov_b32 m0, s31
	ds_read_b128 v[202:205], v143 offset:49152
	ds_read_b128 v[206:209], v143 offset:50176
	ds_read_b128 v[210:213], v143 offset:51200
	ds_read_b128 v[214:217], v143 offset:52224
	ds_read_b128 v[218:221], v143 offset:53248
	ds_read_b128 v[222:225], v143 offset:54272
	ds_read_b128 v[226:229], v143 offset:55296
	ds_read_b128 v[230:233], v143 offset:56320
	global_load_lds_dwordx4 v[138:139], off
	s_add_i32 m0, s31, 0x2000
	s_add_u32 s58, s58, 0x40080
	v_lshl_add_u64 v[138:139], v[168:169], 0, s[22:23]
	s_addc_u32 s59, s59, 0
	s_add_i32 s31, s85, s69
	global_load_lds_dwordx4 v[138:139], off
	v_lshl_add_u64 v[138:139], s[58:59], 0, v[150:151]
	s_mov_b32 m0, s31
	s_nop 0
	global_load_lds_dwordx4 v[138:139], off
	v_lshl_add_u64 v[138:139], s[58:59], 0, v[128:129]
	s_add_i32 m0, s31, 0x2000
	s_nop 0
	global_load_lds_dwordx4 v[138:139], off
	v_lshl_add_u64 v[138:139], v[234:235], 0, s[22:23]
	s_mov_b32 m0, s79
	s_nop 0
	global_load_lds_dwordx4 v[138:139], off
	v_lshl_add_u64 v[138:139], v[236:237], 0, s[22:23]
	s_mov_b32 m0, s80
	s_nop 0
	global_load_lds_dwordx4 v[138:139], off
	s_waitcnt vmcnt(8)
	s_waitcnt lgkmcnt(0)
	s_barrier
	s_waitcnt lgkmcnt(0)
	v_mfma_f32_16x16x32_f16 v[60:63], v[144:147], v[202:205], v[60:63]
	v_mfma_f32_16x16x32_f16 v[52:55], v[160:163], v[202:205], v[52:55]
	v_mfma_f32_16x16x32_f16 v[44:47], v[144:147], v[210:213], v[44:47]
	v_mfma_f32_16x16x32_f16 v[36:39], v[160:163], v[210:213], v[36:39]
	v_mfma_f32_16x16x32_f16 v[28:31], v[144:147], v[218:221], v[28:31]
	v_mfma_f32_16x16x32_f16 v[20:23], v[160:163], v[218:221], v[20:23]
	v_mfma_f32_16x16x32_f16 v[12:15], v[144:147], v[226:229], v[12:15]
	v_mfma_f32_16x16x32_f16 v[4:7], v[160:163], v[226:229], v[4:7]
	v_mfma_f32_16x16x32_f16 v[60:63], v[156:159], v[206:209], v[60:63]
	v_mfma_f32_16x16x32_f16 v[52:55], v[164:167], v[206:209], v[52:55]
	v_mfma_f32_16x16x32_f16 v[44:47], v[156:159], v[214:217], v[44:47]
	v_mfma_f32_16x16x32_f16 v[36:39], v[164:167], v[214:217], v[36:39]
	v_mfma_f32_16x16x32_f16 v[28:31], v[156:159], v[222:225], v[28:31]
	v_mfma_f32_16x16x32_f16 v[20:23], v[164:167], v[222:225], v[20:23]
	v_mfma_f32_16x16x32_f16 v[12:15], v[156:159], v[230:233], v[12:15]
	v_mfma_f32_16x16x32_f16 v[4:7], v[164:167], v[230:233], v[4:7]
	v_mfma_f32_16x16x32_f16 v[56:59], v[186:189], v[202:205], v[56:59]
	v_mfma_f32_16x16x32_f16 v[48:51], v[194:197], v[202:205], v[48:51]
	v_mfma_f32_16x16x32_f16 v[40:43], v[186:189], v[210:213], v[40:43]
	v_mfma_f32_16x16x32_f16 v[32:35], v[194:197], v[210:213], v[32:35]
	v_mfma_f32_16x16x32_f16 v[24:27], v[186:189], v[218:221], v[24:27]
	v_mfma_f32_16x16x32_f16 v[16:19], v[194:197], v[218:221], v[16:19]
	v_mfma_f32_16x16x32_f16 v[8:11], v[186:189], v[226:229], v[8:11]
	v_mfma_f32_16x16x32_f16 v[0:3], v[194:197], v[226:229], v[0:3]
	v_mfma_f32_16x16x32_f16 v[56:59], v[190:193], v[206:209], v[56:59]
	v_mfma_f32_16x16x32_f16 v[48:51], v[198:201], v[206:209], v[48:51]
	v_mfma_f32_16x16x32_f16 v[40:43], v[190:193], v[214:217], v[40:43]
	v_mfma_f32_16x16x32_f16 v[32:35], v[198:201], v[214:217], v[32:35]
	v_mfma_f32_16x16x32_f16 v[24:27], v[190:193], v[222:225], v[24:27]
	v_mfma_f32_16x16x32_f16 v[16:19], v[198:201], v[222:225], v[16:19]
	v_mfma_f32_16x16x32_f16 v[8:11], v[190:193], v[230:233], v[8:11]
	v_mfma_f32_16x16x32_f16 v[0:3], v[198:201], v[230:233], v[0:3]
	s_barrier
	s_add_i32 s30, s30, 2
	s_add_u32 s56, s56, 0x100
	s_addc_u32 s57, s57, 0
	s_add_u32 s83, s83, 0x100
	s_addc_u32 s84, s84, 0
	s_cmp_gt_u32 s30, 13
	s_cbranch_scc0 .LBB0_515
	s_and_b64 vcc, exec, s[16:17]
	s_cbranch_vccz .LBB0_518
	s_barrier

; #define PG8_STAGE(bufoff, gbase, voff) do { _Pragma("unroll") for (int _i = 0; _i < 2; ++_i) \
;         __builtin_amdgcn_global_load_lds((const unsigned*)((const char*)(gbase) + (voff)[_i]), (PG8_LAS unsigned*)(lds + (bufoff) + ldsw + _i * 8192), 16, 0, 0); } while (0)
; #define PG8_LDA(dst, b, h) do { _Pragma("unroll") for (int m = 0; m < 4; ++m) _Pragma("unroll") for (int k = 0; k < 2; ++k) dst[m][k] = *(const PG8_LAS bf16x8*)(lds + PG8_SA(b, h) + aoff + m * 2048 + k * 1024); } while (0)
; #define PG8_LDB(dst, b, h) do { _Pragma("unroll") for (int n = 0; n < 2; ++n) _Pragma("unroll") for (int k = 0; k < 2; ++k) dst[n][k] = *(const PG8_LAS bf16x8*)(lds + PG8_SB(b, h) + boff + n * 2048 + k * 1024); } while (0)
; #define PG8_WAIT_V(n) asm volatile("s_waitcnt vmcnt(" #n ")" ::: "memory")
; #define PG8_WAIT_L(n) asm volatile("s_waitcnt lgkmcnt(" #n ")" ::: "memory")
; #define PG8_BAR __builtin_amdgcn_s_barrier()
; #define PG8_SCHED __builtin_amdgcn_sched_barrier(0)
; template <class Epi, class Sched, bool ALIGN_EPI = false, bool SP2 = false, bool F16 = false>
; __device__ __forceinline__ void gemm_phase(PG8_LAS unsigned char* lds, const Gemm g, const Sched& S, const Epi& E) {
;     ...
;             if constexpr (SP2) {
;             PG8_LDB(B0, 0, 0); PG8_LDB(B1, 0, 1); PG8_SCHED; PG8_LDA(At, 0, 0); PG8_STAGE(PG8_SA(1, 1), a1 + hstep, voffA);
;             PG8_WAIT_V(8); PG8_WAIT_L(0); PG8_BAR; PG8_MMA(0, 0, At, B0); PG8_MMA(0, 1, At, B1); PG8_BAR; PG8_SCHED;
;             PG8_LDA(At, 0, 1); PG8_STAGE(PG8_SB(0, 0), b2, voffB); PG8_STAGE(PG8_SB(0, 1), b2 + hstep, voffB); PG8_STAGE(PG8_SA(0, 0), a2, voffA);
;             PG8_WAIT_V(8); PG8_WAIT_L(0); PG8_BAR; PG8_MMA(1, 0, At, B0); PG8_MMA(1, 1, At, B1); PG8_BAR; PG8_SCHED;
.LBB0_600:
	s_add_u32 s52, s50, 0x100
	s_addc_u32 s53, s51, 0
	s_add_i32 s31, 0, 0x10000
	s_cmp_eq_u32 s30, 40
	s_cselect_b32 s57, s7, s53
	s_cselect_b32 s56, s6, s52
	v_add_u32_e32 v138, s31, v141
	s_cselect_b32 s55, s49, s82
	s_cselect_b32 s54, s48, s81
	s_add_i32 s83, 0, 0x14000
	ds_read_b128 v[144:147], v138
	ds_read_b128 v[156:159], v138 offset:1024
	ds_read_b128 v[160:163], v138 offset:2048
	ds_read_b128 v[164:167], v138 offset:3072
	v_add_u32_e32 v138, s83, v141
	ds_read_b128 v[186:189], v138
	ds_read_b128 v[190:193], v138 offset:1024
	ds_read_b128 v[194:197], v138 offset:2048
	ds_read_b128 v[198:201], v138 offset:3072
	v_lshl_add_u64 v[138:139], s[50:51], 0, v[134:135]
	s_add_i32 m0, s65, 0xc000
	ds_read_b128 v[202:205], v143
	ds_read_b128 v[206:209], v143 offset:1024
	ds_read_b128 v[210:213], v143 offset:2048
	ds_read_b128 v[214:217], v143 offset:3072
	ds_read_b128 v[218:221], v143 offset:4096
	ds_read_b128 v[222:225], v143 offset:5120
	ds_read_b128 v[226:229], v143 offset:6144
	ds_read_b128 v[230:233], v143 offset:7168
	global_load_lds_dwordx4 v[138:139], off
	v_lshl_add_u64 v[138:139], s[50:51], 0, v[136:137]
	s_add_i32 m0, s65, 0xe000
	s_nop 0
	global_load_lds_dwordx4 v[138:139], off
	s_waitcnt vmcnt(8)
	s_waitcnt lgkmcnt(0)
	s_barrier
	s_waitcnt lgkmcnt(0)
	v_mfma_f32_16x16x32_bf16 v[124:127], v[144:147], v[202:205], v[124:127]
	v_mfma_f32_16x16x32_bf16 v[120:123], v[160:163], v[202:205], v[120:123]
	v_mfma_f32_16x16x32_bf16 v[116:119], v[144:147], v[210:213], v[116:119]
	v_mfma_f32_16x16x32_bf16 v[108:111], v[160:163], v[210:213], v[108:111]
	v_mfma_f32_16x16x32_bf16 v[100:103], v[144:147], v[218:221], v[100:103]
	v_mfma_f32_16x16x32_bf16 v[92:95], v[160:163], v[218:221], v[92:95]
	v_mfma_f32_16x16x32_bf16 v[84:87], v[144:147], v[226:229], v[84:87]
	v_mfma_f32_16x16x32_bf16 v[76:79], v[160:163], v[226:229], v[76:79]
	v_mfma_f32_16x16x32_bf16 v[124:127], v[156:159], v[206:209], v[124:127]
	v_mfma_f32_16x16x32_bf16 v[120:123], v[164:167], v[206:209], v[120:123]
	v_mfma_f32_16x16x32_bf16 v[116:119], v[156:159], v[214:217], v[116:119]
	v_mfma_f32_16x16x32_bf16 v[108:111], v[164:167], v[214:217], v[108:111]
	v_mfma_f32_16x16x32_bf16 v[100:103], v[156:159], v[222:225], v[100:103]
	v_mfma_f32_16x16x32_bf16 v[92:95], v[164:167], v[222:225], v[92:95]
	v_mfma_f32_16x16x32_bf16 v[84:87], v[156:159], v[230:233], v[84:87]
	v_mfma_f32_16x16x32_bf16 v[76:79], v[164:167], v[230:233], v[76:79]
	v_mfma_f32_16x16x32_bf16 v[112:115], v[186:189], v[202:205], v[112:115]
	v_mfma_f32_16x16x32_bf16 v[104:107], v[194:197], v[202:205], v[104:107]
	v_mfma_f32_16x16x32_bf16 v[96:99], v[186:189], v[210:213], v[96:99]
	v_mfma_f32_16x16x32_bf16 v[88:91], v[194:197], v[210:213], v[88:91]
	v_mfma_f32_16x16x32_bf16 v[80:83], v[186:189], v[218:221], v[80:83]
	v_mfma_f32_16x16x32_bf16 v[72:75], v[194:197], v[218:221], v[72:75]
	v_mfma_f32_16x16x32_bf16 v[68:71], v[186:189], v[226:229], v[68:71]
	v_mfma_f32_16x16x32_bf16 v[64:67], v[194:197], v[226:229], v[64:67]
	v_mfma_f32_16x16x32_bf16 v[112:115], v[190:193], v[206:209], v[112:115]
	v_mfma_f32_16x16x32_bf16 v[104:107], v[198:201], v[206:209], v[104:107]
	v_mfma_f32_16x16x32_bf16 v[96:99], v[190:193], v[214:217], v[96:99]
	v_mfma_f32_16x16x32_bf16 v[88:91], v[198:201], v[214:217], v[88:91]
	v_mfma_f32_16x16x32_bf16 v[80:83], v[190:193], v[222:225], v[80:83]
	v_mfma_f32_16x16x32_bf16 v[72:75], v[198:201], v[222:225], v[72:75]
	v_mfma_f32_16x16x32_bf16 v[68:71], v[190:193], v[230:233], v[68:71]
	v_mfma_f32_16x16x32_bf16 v[64:67], v[198:201], v[230:233], v[64:67]
	s_barrier
	s_add_i32 s31, s31, s59
	v_lshl_add_u64 v[138:139], s[54:55], 0, v[150:151]
	s_mov_b32 m0, s31
	ds_read_b128 v[202:205], v143 offset:16384
	ds_read_b128 v[206:209], v143 offset:17408
	ds_read_b128 v[210:213], v143 offset:18432
	ds_read_b128 v[214:217], v143 offset:19456
	ds_read_b128 v[218:221], v143 offset:20480
	ds_read_b128 v[222:225], v143 offset:21504
	ds_read_b128 v[226:229], v143 offset:22528
	ds_read_b128 v[230:233], v143 offset:23552
	global_load_lds_dwordx4 v[138:139], off
	s_add_i32 m0, s31, 0x2000
	s_add_u32 s50, s54, 0xb0000
	v_lshl_add_u64 v[168:169], s[54:55], 0, v[128:129]
	s_addc_u32 s51, s55, 0
	s_add_i32 s31, s83, s59
	global_load_lds_dwordx4 v[168:169], off
	v_lshl_add_u64 v[234:235], s[50:51], 0, v[150:151]
	s_mov_b32 m0, s31
	v_lshl_add_u64 v[236:237], s[56:57], 0, v[130:131]
	global_load_lds_dwordx4 v[234:235], off
	v_lshl_add_u64 v[234:235], s[50:51], 0, v[128:129]
	s_add_i32 m0, s31, 0x2000
	s_nop 0
	global_load_lds_dwordx4 v[234:235], off
	v_lshl_add_u64 v[234:235], s[56:57], 0, v[132:133]
	s_mov_b32 m0, s65
	s_nop 0
	global_load_lds_dwordx4 v[234:235], off
	s_mov_b32 m0, s66
	s_nop 0
	global_load_lds_dwordx4 v[236:237], off
	s_waitcnt vmcnt(8)
	s_waitcnt lgkmcnt(0)
	s_barrier
; #define PG8_STAGE(bufoff, gbase, voff) do { _Pragma("unroll") for (int _i = 0; _i < 2; ++_i) \
;         __builtin_amdgcn_global_load_lds((const unsigned*)((const char*)(gbase) + (voff)[_i]), (PG8_LAS unsigned*)(lds + (bufoff) + ldsw + _i * 8192), 16, 0, 0); } while (0)
; #define PG8_LDA(dst, b, h) do { _Pragma("unroll") for (int m = 0; m < 4; ++m) _Pragma("unroll") for (int k = 0; k < 2; ++k) dst[m][k] = *(const PG8_LAS bf16x8*)(lds + PG8_SA(b, h) + aoff + m * 2048 + k * 1024); } while (0)
; #define PG8_LDB(dst, b, h) do { _Pragma("unroll") for (int n = 0; n < 2; ++n) _Pragma("unroll") for (int k = 0; k < 2; ++k) dst[n][k] = *(const PG8_LAS bf16x8*)(lds + PG8_SB(b, h) + boff + n * 2048 + k * 1024); } while (0)
; #define PG8_WAIT_V(n) asm volatile("s_waitcnt vmcnt(" #n ")" ::: "memory")
; #define PG8_WAIT_L(n) asm volatile("s_waitcnt lgkmcnt(" #n ")" ::: "memory")
; #define PG8_BAR __builtin_amdgcn_s_barrier()
; #define PG8_SCHED __builtin_amdgcn_sched_barrier(0)
; template <class Epi, class Sched, bool ALIGN_EPI = false, bool SP2 = false, bool F16 = false>
; __device__ __forceinline__ void gemm_phase(PG8_LAS unsigned char* lds, const Gemm g, const Sched& S, const Epi& E) {
;     ...
;             PG8_WAIT_V(8); PG8_WAIT_L(0); PG8_BAR; PG8_MMA(1, 0, At, B0); PG8_MMA(1, 1, At, B1); PG8_BAR; PG8_SCHED;
;             PG8_LDB(B0, 1, 0); PG8_LDB(B1, 1, 1); PG8_SCHED; PG8_LDA(At, 1, 0); PG8_STAGE(PG8_SA(0, 1), a2 + hstep, voffA);
;             PG8_WAIT_V(8); PG8_WAIT_L(0); PG8_BAR; PG8_MMA(0, 0, At, B0); PG8_MMA(0, 1, At, B1); PG8_BAR; PG8_SCHED;
;             PG8_LDA(At, 1, 1); PG8_STAGE(PG8_SB(1, 0), b3, voffB); PG8_STAGE(PG8_SB(1, 1), b3 + hstep, voffB); PG8_STAGE(PG8_SA(1, 0), a3, voffA);
	s_waitcnt lgkmcnt(0)
	v_mfma_f32_16x16x32_bf16 v[60:63], v[144:147], v[202:205], v[60:63]
	v_mfma_f32_16x16x32_bf16 v[56:59], v[160:163], v[202:205], v[56:59]
	v_mfma_f32_16x16x32_bf16 v[52:55], v[144:147], v[210:213], v[52:55]
	v_mfma_f32_16x16x32_bf16 v[44:47], v[160:163], v[210:213], v[44:47]
	v_mfma_f32_16x16x32_bf16 v[36:39], v[144:147], v[218:221], v[36:39]
	v_mfma_f32_16x16x32_bf16 v[28:31], v[160:163], v[218:221], v[28:31]
	v_mfma_f32_16x16x32_bf16 v[20:23], v[144:147], v[226:229], v[20:23]
	v_mfma_f32_16x16x32_bf16 v[12:15], v[160:163], v[226:229], v[12:15]
	v_mfma_f32_16x16x32_bf16 v[60:63], v[156:159], v[206:209], v[60:63]
	v_mfma_f32_16x16x32_bf16 v[56:59], v[164:167], v[206:209], v[56:59]
	v_mfma_f32_16x16x32_bf16 v[52:55], v[156:159], v[214:217], v[52:55]
	v_mfma_f32_16x16x32_bf16 v[44:47], v[164:167], v[214:217], v[44:47]
	v_mfma_f32_16x16x32_bf16 v[36:39], v[156:159], v[222:225], v[36:39]
	v_mfma_f32_16x16x32_bf16 v[28:31], v[164:167], v[222:225], v[28:31]
	v_mfma_f32_16x16x32_bf16 v[20:23], v[156:159], v[230:233], v[20:23]
	v_mfma_f32_16x16x32_bf16 v[12:15], v[164:167], v[230:233], v[12:15]
	v_mfma_f32_16x16x32_bf16 v[48:51], v[186:189], v[202:205], v[48:51]
	v_mfma_f32_16x16x32_bf16 v[40:43], v[194:197], v[202:205], v[40:43]
	v_mfma_f32_16x16x32_bf16 v[32:35], v[186:189], v[210:213], v[32:35]
	v_mfma_f32_16x16x32_bf16 v[24:27], v[194:197], v[210:213], v[24:27]
	v_mfma_f32_16x16x32_bf16 v[16:19], v[186:189], v[218:221], v[16:19]
	v_mfma_f32_16x16x32_bf16 v[8:11], v[194:197], v[218:221], v[8:11]
	v_mfma_f32_16x16x32_bf16 v[4:7], v[186:189], v[226:229], v[4:7]
	v_mfma_f32_16x16x32_bf16 v[0:3], v[194:197], v[226:229], v[0:3]
	v_mfma_f32_16x16x32_bf16 v[48:51], v[190:193], v[206:209], v[48:51]
	v_mfma_f32_16x16x32_bf16 v[40:43], v[198:201], v[206:209], v[40:43]
	v_mfma_f32_16x16x32_bf16 v[32:35], v[190:193], v[214:217], v[32:35]
	v_mfma_f32_16x16x32_bf16 v[24:27], v[198:201], v[214:217], v[24:27]
	v_mfma_f32_16x16x32_bf16 v[16:19], v[190:193], v[222:225], v[16:19]
	v_mfma_f32_16x16x32_bf16 v[8:11], v[198:201], v[222:225], v[8:11]
	v_mfma_f32_16x16x32_bf16 v[4:7], v[190:193], v[230:233], v[4:7]
	v_mfma_f32_16x16x32_bf16 v[0:3], v[198:201], v[230:233], v[0:3]
	s_barrier
	s_add_i32 s31, 0, 0x18000
	s_add_i32 s83, 0, 0x1c000
	v_add_u32_e32 v164, s31, v141
	v_add_u32_e32 v170, s83, v141
	ds_read_b128 v[144:147], v164
	ds_read_b128 v[156:159], v164 offset:1024
	ds_read_b128 v[160:163], v164 offset:2048
	ds_read_b128 v[164:167], v164 offset:3072
	ds_read_b128 v[186:189], v170
	ds_read_b128 v[190:193], v170 offset:1024
	ds_read_b128 v[194:197], v170 offset:2048
	ds_read_b128 v[198:201], v170 offset:3072
	s_add_u32 s50, s56, 0xb0000
	s_addc_u32 s51, s57, 0
	s_mov_b32 m0, s67
	v_lshl_add_u64 v[238:239], s[50:51], 0, v[132:133]
	ds_read_b128 v[202:205], v143 offset:32768
	ds_read_b128 v[206:209], v143 offset:33792
	ds_read_b128 v[210:213], v143 offset:34816
	ds_read_b128 v[214:217], v143 offset:35840
	ds_read_b128 v[218:221], v143 offset:36864
	ds_read_b128 v[222:225], v143 offset:37888
	ds_read_b128 v[226:229], v143 offset:38912
	ds_read_b128 v[230:233], v143 offset:39936
	global_load_lds_dwordx4 v[238:239], off
	v_lshl_add_u64 v[238:239], s[50:51], 0, v[130:131]
	s_mov_b32 m0, s68
	s_nop 0
	global_load_lds_dwordx4 v[238:239], off
	s_waitcnt vmcnt(8)
	s_waitcnt lgkmcnt(0)
	s_barrier
	s_waitcnt lgkmcnt(0)
	v_mfma_f32_16x16x32_bf16 v[124:127], v[144:147], v[202:205], v[124:127]
	v_mfma_f32_16x16x32_bf16 v[120:123], v[160:163], v[202:205], v[120:123]
	v_mfma_f32_16x16x32_bf16 v[116:119], v[144:147], v[210:213], v[116:119]
	v_mfma_f32_16x16x32_bf16 v[108:111], v[160:163], v[210:213], v[108:111]
	v_mfma_f32_16x16x32_bf16 v[100:103], v[144:147], v[218:221], v[100:103]
	v_mfma_f32_16x16x32_bf16 v[92:95], v[160:163], v[218:221], v[92:95]
	v_mfma_f32_16x16x32_bf16 v[84:87], v[144:147], v[226:229], v[84:87]
	v_mfma_f32_16x16x32_bf16 v[76:79], v[160:163], v[226:229], v[76:79]
	v_mfma_f32_16x16x32_bf16 v[124:127], v[156:159], v[206:209], v[124:127]
	v_mfma_f32_16x16x32_bf16 v[120:123], v[164:167], v[206:209], v[120:123]
	v_mfma_f32_16x16x32_bf16 v[116:119], v[156:159], v[214:217], v[116:119]
	v_mfma_f32_16x16x32_bf16 v[108:111], v[164:167], v[214:217], v[108:111]
	v_mfma_f32_16x16x32_bf16 v[100:103], v[156:159], v[222:225], v[100:103]
	v_mfma_f32_16x16x32_bf16 v[92:95], v[164:167], v[222:225], v[92:95]
	v_mfma_f32_16x16x32_bf16 v[84:87], v[156:159], v[230:233], v[84:87]
	v_mfma_f32_16x16x32_bf16 v[76:79], v[164:167], v[230:233], v[76:79]
	v_mfma_f32_16x16x32_bf16 v[112:115], v[186:189], v[202:205], v[112:115]
	v_mfma_f32_16x16x32_bf16 v[104:107], v[194:197], v[202:205], v[104:107]
	v_mfma_f32_16x16x32_bf16 v[96:99], v[186:189], v[210:213], v[96:99]
	v_mfma_f32_16x16x32_bf16 v[88:91], v[194:197], v[210:213], v[88:91]
	v_mfma_f32_16x16x32_bf16 v[80:83], v[186:189], v[218:221], v[80:83]
	v_mfma_f32_16x16x32_bf16 v[72:75], v[194:197], v[218:221], v[72:75]
	v_mfma_f32_16x16x32_bf16 v[68:71], v[186:189], v[226:229], v[68:71]
	v_mfma_f32_16x16x32_bf16 v[64:67], v[194:197], v[226:229], v[64:67]
	v_mfma_f32_16x16x32_bf16 v[112:115], v[190:193], v[206:209], v[112:115]
	v_mfma_f32_16x16x32_bf16 v[104:107], v[198:201], v[206:209], v[104:107]
	v_mfma_f32_16x16x32_bf16 v[96:99], v[190:193], v[214:217], v[96:99]
	v_mfma_f32_16x16x32_bf16 v[88:91], v[198:201], v[214:217], v[88:91]
	v_mfma_f32_16x16x32_bf16 v[80:83], v[190:193], v[222:225], v[80:83]
	v_mfma_f32_16x16x32_bf16 v[72:75], v[198:201], v[222:225], v[72:75]
	v_mfma_f32_16x16x32_bf16 v[68:71], v[190:193], v[230:233], v[68:71]
	v_mfma_f32_16x16x32_bf16 v[64:67], v[198:201], v[230:233], v[64:67]
	s_barrier
; #define PG8_STAGE(bufoff, gbase, voff) do { _Pragma("unroll") for (int _i = 0; _i < 2; ++_i) \
;         __builtin_amdgcn_global_load_lds((const unsigned*)((const char*)(gbase) + (voff)[_i]), (PG8_LAS unsigned*)(lds + (bufoff) + ldsw + _i * 8192), 16, 0, 0); } while (0)
; #define PG8_LDA(dst, b, h) do { _Pragma("unroll") for (int m = 0; m < 4; ++m) _Pragma("unroll") for (int k = 0; k < 2; ++k) dst[m][k] = *(const PG8_LAS bf16x8*)(lds + PG8_SA(b, h) + aoff + m * 2048 + k * 1024); } while (0)
; #define PG8_WAIT_V(n) asm volatile("s_waitcnt vmcnt(" #n ")" ::: "memory")
; #define PG8_WAIT_L(n) asm volatile("s_waitcnt lgkmcnt(" #n ")" ::: "memory")
; #define PG8_BAR __builtin_amdgcn_s_barrier()
; #define PG8_SCHED __builtin_amdgcn_sched_barrier(0)
; template <class Epi, class Sched, bool ALIGN_EPI = false, bool SP2 = false, bool F16 = false>
; __device__ __forceinline__ void gemm_phase(PG8_LAS unsigned char* lds, const Gemm g, const Sched& S, const Epi& E) {
;     ...
;         for (int t = 0; t < nt; t += 2) {
;     ...
;             PG8_LDA(At, 1, 1); PG8_STAGE(PG8_SB(1, 0), b3, voffB); PG8_STAGE(PG8_SB(1, 1), b3 + hstep, voffB); PG8_STAGE(PG8_SA(1, 0), a3, voffA);
;             PG8_WAIT_V(8); PG8_WAIT_L(0); PG8_BAR; PG8_MMA(1, 0, At, B0); PG8_MMA(1, 1, At, B1); PG8_BAR; PG8_SCHED;
	s_add_i32 s31, s31, s59
	v_lshl_add_u64 v[138:139], v[138:139], 0, s[22:23]
	s_mov_b32 m0, s31
	ds_read_b128 v[202:205], v143 offset:49152
	ds_read_b128 v[206:209], v143 offset:50176
	ds_read_b128 v[210:213], v143 offset:51200
	ds_read_b128 v[214:217], v143 offset:52224
	ds_read_b128 v[218:221], v143 offset:53248
	ds_read_b128 v[222:225], v143 offset:54272
	ds_read_b128 v[226:229], v143 offset:55296
	ds_read_b128 v[230:233], v143 offset:56320
	global_load_lds_dwordx4 v[138:139], off
	s_add_i32 m0, s31, 0x2000
	s_add_u32 s50, s54, 0xb0080
	v_lshl_add_u64 v[138:139], v[168:169], 0, s[22:23]
	s_addc_u32 s51, s55, 0
	s_add_i32 s31, s83, s59
	global_load_lds_dwordx4 v[138:139], off
	v_lshl_add_u64 v[138:139], s[50:51], 0, v[150:151]
	s_mov_b32 m0, s31
	s_nop 0
	global_load_lds_dwordx4 v[138:139], off
	v_lshl_add_u64 v[138:139], s[50:51], 0, v[128:129]
	s_add_i32 m0, s31, 0x2000
	s_nop 0
	global_load_lds_dwordx4 v[138:139], off
	v_lshl_add_u64 v[138:139], v[234:235], 0, s[22:23]
	s_mov_b32 m0, s74
	s_nop 0
	global_load_lds_dwordx4 v[138:139], off
	v_lshl_add_u64 v[138:139], v[236:237], 0, s[22:23]
	s_mov_b32 m0, s75
	s_nop 0
	global_load_lds_dwordx4 v[138:139], off
	s_waitcnt vmcnt(8)
	s_waitcnt lgkmcnt(0)
	s_barrier
	s_waitcnt lgkmcnt(0)
	v_mfma_f32_16x16x32_bf16 v[60:63], v[144:147], v[202:205], v[60:63]
	v_mfma_f32_16x16x32_bf16 v[56:59], v[160:163], v[202:205], v[56:59]
	v_mfma_f32_16x16x32_bf16 v[52:55], v[144:147], v[210:213], v[52:55]
	v_mfma_f32_16x16x32_bf16 v[44:47], v[160:163], v[210:213], v[44:47]
	v_mfma_f32_16x16x32_bf16 v[36:39], v[144:147], v[218:221], v[36:39]
	v_mfma_f32_16x16x32_bf16 v[28:31], v[160:163], v[218:221], v[28:31]
	v_mfma_f32_16x16x32_bf16 v[20:23], v[144:147], v[226:229], v[20:23]
	v_mfma_f32_16x16x32_bf16 v[12:15], v[160:163], v[226:229], v[12:15]
	v_mfma_f32_16x16x32_bf16 v[60:63], v[156:159], v[206:209], v[60:63]
	v_mfma_f32_16x16x32_bf16 v[56:59], v[164:167], v[206:209], v[56:59]
	v_mfma_f32_16x16x32_bf16 v[52:55], v[156:159], v[214:217], v[52:55]
	v_mfma_f32_16x16x32_bf16 v[44:47], v[164:167], v[214:217], v[44:47]
	v_mfma_f32_16x16x32_bf16 v[36:39], v[156:159], v[222:225], v[36:39]
	v_mfma_f32_16x16x32_bf16 v[28:31], v[164:167], v[222:225], v[28:31]
	v_mfma_f32_16x16x32_bf16 v[20:23], v[156:159], v[230:233], v[20:23]
	v_mfma_f32_16x16x32_bf16 v[12:15], v[164:167], v[230:233], v[12:15]
	v_mfma_f32_16x16x32_bf16 v[48:51], v[186:189], v[202:205], v[48:51]
	v_mfma_f32_16x16x32_bf16 v[40:43], v[194:197], v[202:205], v[40:43]
	v_mfma_f32_16x16x32_bf16 v[32:35], v[186:189], v[210:213], v[32:35]
	v_mfma_f32_16x16x32_bf16 v[24:27], v[194:197], v[210:213], v[24:27]
	v_mfma_f32_16x16x32_bf16 v[16:19], v[186:189], v[218:221], v[16:19]
	v_mfma_f32_16x16x32_bf16 v[8:11], v[194:197], v[218:221], v[8:11]
	v_mfma_f32_16x16x32_bf16 v[4:7], v[186:189], v[226:229], v[4:7]
	v_mfma_f32_16x16x32_bf16 v[0:3], v[194:197], v[226:229], v[0:3]
	v_mfma_f32_16x16x32_bf16 v[48:51], v[190:193], v[206:209], v[48:51]
	v_mfma_f32_16x16x32_bf16 v[40:43], v[198:201], v[206:209], v[40:43]
	v_mfma_f32_16x16x32_bf16 v[32:35], v[190:193], v[214:217], v[32:35]
	v_mfma_f32_16x16x32_bf16 v[24:27], v[198:201], v[214:217], v[24:27]
	v_mfma_f32_16x16x32_bf16 v[16:19], v[190:193], v[222:225], v[16:19]
	v_mfma_f32_16x16x32_bf16 v[8:11], v[198:201], v[222:225], v[8:11]
	v_mfma_f32_16x16x32_bf16 v[4:7], v[190:193], v[230:233], v[4:7]
	v_mfma_f32_16x16x32_bf16 v[0:3], v[198:201], v[230:233], v[0:3]
	s_barrier
	s_add_i32 s30, s30, 2
	s_add_u32 s81, s81, 0x100
	s_addc_u32 s82, s82, 0
	s_cmp_gt_u32 s30, 41
	s_mov_b64 s[50:51], s[52:53]
	s_cbranch_scc0 .LBB0_600
	s_and_b64 vcc, exec, s[18:19]
	s_cbranch_vccz .LBB0_603
	s_barrier
